# speedup vs baseline: 1.0121x; 1.0048x over previous
; #define MFMA32(a, b, c) __builtin_amdgcn_mfma_f32_32x32x16_bf16((a), (b), (c), 0, 0, 0)
; template <int AMODE, bool SWAP>
; DI void gemm_core(const u16* __restrict__ A, int lda, const u16* __restrict__ Bt, int ldb, int K, int m0, int n0, int acol,
;                   f32x16 (&acc)[2][2], u16* sA, u16* sB) {
;     ...
;   auto stage = [&](const u32x4 (&xa)[4], const u32x4 (&xb)[4]) {
; #pragma unroll
;     for (int i = 0; i < 4; ++i) {
;       const int id = tid + 256 * i, row = id >> 3, ch = id & 7;
;       *reinterpret_cast<u32x4*>(sA + row * LDT + ch * 8) = xa[i];
;       *reinterpret_cast<u32x4*>(sB + row * LDT + ch * 8) = xb[i];
;     }
;   };
;   auto ldfrag = [&](int ks, bf16x8 (&af)[2], bf16x8 (&bfr)[2]) {
; #pragma unroll
;     for (int t = 0; t < 2; ++t) {
;       af[t] = ld16(sA + (wm * 64 + t * 32 + r) * LDT + ks * 16 + h2 * 8);
;       bfr[t] = ld16(sB + (wn * 64 + t * 32 + r) * LDT + ks * 16 + h2 * 8);
;     }
;   };
;   auto mm = [&](const bf16x8 (&af)[2], const bf16x8 (&bfr)[2]) {
; #pragma unroll
;     for (int mt = 0; mt < 2; ++mt)
; #pragma unroll
;       for (int nt = 0; nt < 2; ++nt) {
;         if (SWAP) acc[mt][nt] = MFMA32(bfr[nt], af[mt], acc[mt][nt]);
;         else acc[mt][nt] = MFMA32(af[mt], bfr[nt], acc[mt][nt]);
;       }
;   };
;   auto compute = [&]() {
;     bf16x8 a0[2], b0[2], a1[2], b1[2];
;     ldfrag(0, a0, b0);
;     ldfrag(1, a1, b1);
;     __builtin_amdgcn_sched_barrier(0);
;     mm(a0, b0);
;     __builtin_amdgcn_sched_barrier(0);
;     ldfrag(2, a0, b0);
;     __builtin_amdgcn_sched_barrier(0);
;     mm(a1, b1);
;     __builtin_amdgcn_sched_barrier(0);
;     ldfrag(3, a1, b1);
;     __builtin_amdgcn_sched_barrier(0);
;     mm(a0, b0);
;     mm(a1, b1);
.Lmy_p13_loop:
	s_waitcnt vmcnt(8)
	ds_write_b128 v119, v[202:205]
	ds_write_b128 v119, v[206:209] offset:18432
	ds_write_b128 v118, v[210:213]
	ds_write_b128 v118, v[214:217] offset:18432
	ds_write_b128 v117, v[218:221]
	ds_write_b128 v117, v[222:225] offset:18432
	ds_write_b128 v116, v[152:155]
	ds_write_b128 v116, v[160:163] offset:18432
	ds_read_b128 v[120:123], v174
	ds_read_b128 v[124:127], v174 offset:32
	ds_read_b128 v[128:131], v175 offset:18432
	ds_read_b128 v[132:135], v175 offset:18464
	ds_read_b128 v[136:139], v174 offset:4608
	ds_read_b128 v[140:143], v174 offset:4640
	ds_read_b128 v[144:147], v175 offset:23040
	ds_read_b128 v[148:151], v175 offset:23072
	s_waitcnt lgkmcnt(5)
	v_mfma_f32_32x32x16_bf16 v[50:65], v[128:131], v[120:123], v[50:65]
	global_load_dwordx4 v[202:205], v[98:99], off offset:128
	global_load_dwordx4 v[206:209], v[100:101], off offset:128
	global_load_dwordx4 v[210:213], v[102:103], off offset:128
	global_load_dwordx4 v[214:217], v[104:105], off offset:128
	global_load_dwordx4 v[218:221], v[106:107], off offset:128
	global_load_dwordx4 v[222:225], v[108:109], off offset:128
	global_load_dwordx4 v[152:155], v[110:111], off offset:128
	global_load_dwordx4 v[160:163], v[112:113], off offset:128
	v_lshl_add_u64 v[98:99], v[98:99], 0, s[30:31]
	v_lshl_add_u64 v[100:101], v[100:101], 0, s[30:31]
	v_lshl_add_u64 v[102:103], v[102:103], 0, s[30:31]
	v_lshl_add_u64 v[104:105], v[104:105], 0, s[30:31]
	v_lshl_add_u64 v[106:107], v[106:107], 0, s[30:31]
	v_lshl_add_u64 v[108:109], v[108:109], 0, s[30:31]
	v_lshl_add_u64 v[110:111], v[110:111], 0, s[30:31]
	v_lshl_add_u64 v[112:113], v[112:113], 0, s[30:31]
	s_waitcnt lgkmcnt(1)
	v_mfma_f32_32x32x16_bf16 v[34:49], v[144:147], v[120:123], v[34:49]
	v_mfma_f32_32x32x16_bf16 v[18:33], v[128:131], v[136:139], v[18:33]
	v_mfma_f32_32x32x16_bf16 v[2:17], v[144:147], v[136:139], v[2:17]
	ds_read_b128 v[120:123], v174 offset:64
	ds_read_b128 v[128:131], v174 offset:4672
	ds_read_b128 v[136:139], v175 offset:18496
	ds_read_b128 v[144:147], v175 offset:23104
	v_mfma_f32_32x32x16_bf16 v[50:65], v[132:135], v[124:127], v[50:65]
	s_waitcnt lgkmcnt(4)
	v_mfma_f32_32x32x16_bf16 v[34:49], v[148:151], v[124:127], v[34:49]
	v_mfma_f32_32x32x16_bf16 v[18:33], v[132:135], v[140:143], v[18:33]
	v_mfma_f32_32x32x16_bf16 v[2:17], v[148:151], v[140:143], v[2:17]
	ds_read_b128 v[124:127], v174 offset:96
	ds_read_b128 v[132:135], v174 offset:4704
	ds_read_b128 v[140:143], v175 offset:18528
	ds_read_b128 v[148:151], v175 offset:23136
	s_waitcnt lgkmcnt(5)
	v_mfma_f32_32x32x16_bf16 v[50:65], v[136:139], v[120:123], v[50:65]
	s_waitcnt lgkmcnt(0)
	s_barrier
	v_mfma_f32_32x32x16_bf16 v[34:49], v[144:147], v[120:123], v[34:49]
	v_mfma_f32_32x32x16_bf16 v[18:33], v[136:139], v[128:131], v[18:33]
	v_mfma_f32_32x32x16_bf16 v[2:17], v[144:147], v[128:131], v[2:17]
	v_mfma_f32_32x32x16_bf16 v[50:65], v[140:143], v[124:127], v[50:65]
	v_mfma_f32_32x32x16_bf16 v[34:49], v[148:151], v[124:127], v[34:49]
	v_mfma_f32_32x32x16_bf16 v[18:33], v[140:143], v[132:135], v[18:33]
	v_mfma_f32_32x32x16_bf16 v[2:17], v[148:151], v[132:135], v[2:17]
	s_waitcnt vmcnt(8)
	ds_write_b128 v170, v[94:97]
	ds_write_b128 v170, v[86:89] offset:18432
	ds_write_b128 v171, v[90:93]
	ds_write_b128 v171, v[78:81] offset:18432
	ds_write_b128 v172, v[82:85]
	ds_write_b128 v172, v[66:69] offset:18432
	ds_write_b128 v173, v[74:77]
	ds_write_b128 v173, v[70:73] offset:18432
	ds_read_b128 v[120:123], v114
	ds_read_b128 v[124:127], v114 offset:32
	ds_read_b128 v[128:131], v115 offset:18432
	ds_read_b128 v[132:135], v115 offset:18464
	ds_read_b128 v[136:139], v114 offset:4608
	ds_read_b128 v[140:143], v114 offset:4640
	ds_read_b128 v[144:147], v115 offset:23040
	ds_read_b128 v[148:151], v115 offset:23072
	s_waitcnt lgkmcnt(5)
	v_mfma_f32_32x32x16_bf16 v[50:65], v[128:131], v[120:123], v[50:65]
	global_load_dwordx4 v[94:97], v[98:99], off offset:128
	global_load_dwordx4 v[86:89], v[100:101], off offset:128
	global_load_dwordx4 v[90:93], v[102:103], off offset:128
	global_load_dwordx4 v[78:81], v[104:105], off offset:128
	global_load_dwordx4 v[82:85], v[106:107], off offset:128
	global_load_dwordx4 v[66:69], v[108:109], off offset:128
	global_load_dwordx4 v[74:77], v[110:111], off offset:128
	global_load_dwordx4 v[70:73], v[112:113], off offset:128
	v_lshl_add_u64 v[98:99], v[98:99], 0, s[30:31]
	v_lshl_add_u64 v[100:101], v[100:101], 0, s[30:31]
	v_lshl_add_u64 v[102:103], v[102:103], 0, s[30:31]
	v_lshl_add_u64 v[104:105], v[104:105], 0, s[30:31]
	v_lshl_add_u64 v[106:107], v[106:107], 0, s[30:31]
	v_lshl_add_u64 v[108:109], v[108:109], 0, s[30:31]
	v_lshl_add_u64 v[110:111], v[110:111], 0, s[30:31]
	v_lshl_add_u64 v[112:113], v[112:113], 0, s[30:31]
	s_waitcnt lgkmcnt(1)
	v_mfma_f32_32x32x16_bf16 v[34:49], v[144:147], v[120:123], v[34:49]
	v_mfma_f32_32x32x16_bf16 v[18:33], v[128:131], v[136:139], v[18:33]
	v_mfma_f32_32x32x16_bf16 v[2:17], v[144:147], v[136:139], v[2:17]
	ds_read_b128 v[120:123], v114 offset:64
	ds_read_b128 v[128:131], v114 offset:4672
	ds_read_b128 v[136:139], v115 offset:18496
	ds_read_b128 v[144:147], v115 offset:23104
	v_mfma_f32_32x32x16_bf16 v[50:65], v[132:135], v[124:127], v[50:65]
	s_waitcnt lgkmcnt(4)
	v_mfma_f32_32x32x16_bf16 v[34:49], v[148:151], v[124:127], v[34:49]
	v_mfma_f32_32x32x16_bf16 v[18:33], v[132:135], v[140:143], v[18:33]
	v_mfma_f32_32x32x16_bf16 v[2:17], v[148:151], v[140:143], v[2:17]
	ds_read_b128 v[124:127], v114 offset:96
	ds_read_b128 v[132:135], v114 offset:4704
	ds_read_b128 v[140:143], v115 offset:18528
	ds_read_b128 v[148:151], v115 offset:23136
	s_waitcnt lgkmcnt(5)
	v_mfma_f32_32x32x16_bf16 v[50:65], v[136:139], v[120:123], v[50:65]
	s_waitcnt lgkmcnt(0)
	s_barrier
; #define MFMA32(a, b, c) __builtin_amdgcn_mfma_f32_32x32x16_bf16((a), (b), (c), 0, 0, 0)
; template <int AMODE, bool SWAP>
; DI void gemm_core(const u16* __restrict__ A, int lda, const u16* __restrict__ Bt, int ldb, int K, int m0, int n0, int acol,
;                   f32x16 (&acc)[2][2], u16* sA, u16* sB) {
;     ...
;   auto stage = [&](const u32x4 (&xa)[4], const u32x4 (&xb)[4]) {
; #pragma unroll
;     for (int i = 0; i < 4; ++i) {
;       const int id = tid + 256 * i, row = id >> 3, ch = id & 7;
;       *reinterpret_cast<u32x4*>(sA + row * LDT + ch * 8) = xa[i];
;       *reinterpret_cast<u32x4*>(sB + row * LDT + ch * 8) = xb[i];
;     }
;   };
;   auto ldfrag = [&](int ks, bf16x8 (&af)[2], bf16x8 (&bfr)[2]) {
; #pragma unroll
;     for (int t = 0; t < 2; ++t) {
;       af[t] = ld16(sA + (wm * 64 + t * 32 + r) * LDT + ks * 16 + h2 * 8);
;       bfr[t] = ld16(sB + (wn * 64 + t * 32 + r) * LDT + ks * 16 + h2 * 8);
;     }
;   };
;   auto mm = [&](const bf16x8 (&af)[2], const bf16x8 (&bfr)[2]) {
; #pragma unroll
;     for (int mt = 0; mt < 2; ++mt)
; #pragma unroll
;       for (int nt = 0; nt < 2; ++nt) {
;         if (SWAP) acc[mt][nt] = MFMA32(bfr[nt], af[mt], acc[mt][nt]);
;         else acc[mt][nt] = MFMA32(af[mt], bfr[nt], acc[mt][nt]);
;       }
;   };
;   auto compute = [&]() {
;     bf16x8 a0[2], b0[2], a1[2], b1[2];
;     ldfrag(0, a0, b0);
;     ldfrag(1, a1, b1);
;     __builtin_amdgcn_sched_barrier(0);
;     mm(a0, b0);
;     __builtin_amdgcn_sched_barrier(0);
;     ldfrag(2, a0, b0);
;     __builtin_amdgcn_sched_barrier(0);
;     mm(a1, b1);
;     __builtin_amdgcn_sched_barrier(0);
;     ldfrag(3, a1, b1);
;     __builtin_amdgcn_sched_barrier(0);
;     mm(a0, b0);
;     mm(a1, b1);
;   };
;   gload(0, ra[0], rb[0]);
;   for (int kt = 0; kt < nk; ++kt) {
;     stage(ra[0], rb[0]);
;     __syncthreads();
;     if (kt + 1 < nk) gload(kt + 1, ra[0], rb[0]);
;     __builtin_amdgcn_sched_barrier(0);
;     compute();
;     __syncthreads();
;   }
	v_mfma_f32_32x32x16_bf16 v[34:49], v[144:147], v[120:123], v[34:49]
	v_mfma_f32_32x32x16_bf16 v[18:33], v[136:139], v[128:131], v[18:33]
	v_mfma_f32_32x32x16_bf16 v[2:17], v[144:147], v[128:131], v[2:17]
	v_mfma_f32_32x32x16_bf16 v[50:65], v[140:143], v[124:127], v[50:65]
	v_mfma_f32_32x32x16_bf16 v[34:49], v[148:151], v[124:127], v[34:49]
	v_mfma_f32_32x32x16_bf16 v[18:33], v[140:143], v[132:135], v[18:33]
	v_mfma_f32_32x32x16_bf16 v[2:17], v[148:151], v[132:135], v[2:17]
	s_add_i32 s100, s100, 1
	s_cmp_lt_u32 s100, 6
	s_cbranch_scc1 .Lmy_p13_loop
	s_waitcnt vmcnt(8)
	ds_write_b128 v119, v[202:205]
	ds_write_b128 v119, v[206:209] offset:18432
	ds_write_b128 v118, v[210:213]
	ds_write_b128 v118, v[214:217] offset:18432
	ds_write_b128 v117, v[218:221]
	ds_write_b128 v117, v[222:225] offset:18432
	ds_write_b128 v116, v[152:155]
	ds_write_b128 v116, v[160:163] offset:18432
	ds_read_b128 v[120:123], v174
	ds_read_b128 v[124:127], v174 offset:32
	ds_read_b128 v[128:131], v175 offset:18432
	ds_read_b128 v[132:135], v175 offset:18464
	ds_read_b128 v[136:139], v174 offset:4608
	ds_read_b128 v[140:143], v174 offset:4640
	ds_read_b128 v[144:147], v175 offset:23040
	ds_read_b128 v[148:151], v175 offset:23072
	s_waitcnt lgkmcnt(5)
	v_mfma_f32_32x32x16_bf16 v[50:65], v[128:131], v[120:123], v[50:65]
	global_load_dwordx4 v[202:205], v[98:99], off offset:128
	global_load_dwordx4 v[206:209], v[100:101], off offset:128
	global_load_dwordx4 v[210:213], v[102:103], off offset:128
	global_load_dwordx4 v[214:217], v[104:105], off offset:128
	global_load_dwordx4 v[218:221], v[106:107], off offset:128
	global_load_dwordx4 v[222:225], v[108:109], off offset:128
	global_load_dwordx4 v[152:155], v[110:111], off offset:128
	global_load_dwordx4 v[160:163], v[112:113], off offset:128
	v_lshl_add_u64 v[98:99], v[98:99], 0, s[30:31]
	v_lshl_add_u64 v[100:101], v[100:101], 0, s[30:31]
	v_lshl_add_u64 v[102:103], v[102:103], 0, s[30:31]
	v_lshl_add_u64 v[104:105], v[104:105], 0, s[30:31]
	v_lshl_add_u64 v[106:107], v[106:107], 0, s[30:31]
	v_lshl_add_u64 v[108:109], v[108:109], 0, s[30:31]
	v_lshl_add_u64 v[110:111], v[110:111], 0, s[30:31]
	v_lshl_add_u64 v[112:113], v[112:113], 0, s[30:31]
	s_waitcnt lgkmcnt(1)
	v_mfma_f32_32x32x16_bf16 v[34:49], v[144:147], v[120:123], v[34:49]
	v_mfma_f32_32x32x16_bf16 v[18:33], v[128:131], v[136:139], v[18:33]
	v_mfma_f32_32x32x16_bf16 v[2:17], v[144:147], v[136:139], v[2:17]
	ds_read_b128 v[120:123], v174 offset:64
	ds_read_b128 v[128:131], v174 offset:4672
	ds_read_b128 v[136:139], v175 offset:18496
	ds_read_b128 v[144:147], v175 offset:23104
	v_mfma_f32_32x32x16_bf16 v[50:65], v[132:135], v[124:127], v[50:65]
	s_waitcnt lgkmcnt(4)
	v_mfma_f32_32x32x16_bf16 v[34:49], v[148:151], v[124:127], v[34:49]
	v_mfma_f32_32x32x16_bf16 v[18:33], v[132:135], v[140:143], v[18:33]
	v_mfma_f32_32x32x16_bf16 v[2:17], v[148:151], v[140:143], v[2:17]
	ds_read_b128 v[124:127], v174 offset:96
	ds_read_b128 v[132:135], v174 offset:4704
	ds_read_b128 v[140:143], v175 offset:18528
	ds_read_b128 v[148:151], v175 offset:23136
	s_waitcnt lgkmcnt(5)
	v_mfma_f32_32x32x16_bf16 v[50:65], v[136:139], v[120:123], v[50:65]
	s_waitcnt lgkmcnt(0)
	s_barrier
	v_mfma_f32_32x32x16_bf16 v[34:49], v[144:147], v[120:123], v[34:49]
	v_mfma_f32_32x32x16_bf16 v[18:33], v[136:139], v[128:131], v[18:33]
	v_mfma_f32_32x32x16_bf16 v[2:17], v[144:147], v[128:131], v[2:17]
	v_mfma_f32_32x32x16_bf16 v[50:65], v[140:143], v[124:127], v[50:65]
	v_mfma_f32_32x32x16_bf16 v[34:49], v[148:151], v[124:127], v[34:49]
	v_mfma_f32_32x32x16_bf16 v[18:33], v[140:143], v[132:135], v[18:33]
	v_mfma_f32_32x32x16_bf16 v[2:17], v[148:151], v[132:135], v[2:17]
	s_waitcnt vmcnt(8)
	ds_write_b128 v170, v[94:97]
	ds_write_b128 v170, v[86:89] offset:18432
	ds_write_b128 v171, v[90:93]
	ds_write_b128 v171, v[78:81] offset:18432
	ds_write_b128 v172, v[82:85]
	ds_write_b128 v172, v[66:69] offset:18432
	ds_write_b128 v173, v[74:77]
	ds_write_b128 v173, v[70:73] offset:18432
	ds_read_b128 v[120:123], v114
	ds_read_b128 v[124:127], v114 offset:32
	ds_read_b128 v[128:131], v115 offset:18432
	ds_read_b128 v[132:135], v115 offset:18464
	ds_read_b128 v[136:139], v114 offset:4608
	ds_read_b128 v[140:143], v114 offset:4640
	ds_read_b128 v[144:147], v115 offset:23040
	ds_read_b128 v[148:151], v115 offset:23072
	s_waitcnt lgkmcnt(5)
	v_mfma_f32_32x32x16_bf16 v[50:65], v[128:131], v[120:123], v[50:65]
	s_waitcnt lgkmcnt(1)
	v_mfma_f32_32x32x16_bf16 v[34:49], v[144:147], v[120:123], v[34:49]
	v_mfma_f32_32x32x16_bf16 v[18:33], v[128:131], v[136:139], v[18:33]
	v_mfma_f32_32x32x16_bf16 v[2:17], v[144:147], v[136:139], v[2:17]
	ds_read_b128 v[120:123], v114 offset:64
	ds_read_b128 v[128:131], v114 offset:4672
	ds_read_b128 v[136:139], v115 offset:18496
	ds_read_b128 v[144:147], v115 offset:23104
	v_mfma_f32_32x32x16_bf16 v[50:65], v[132:135], v[124:127], v[50:65]
	s_waitcnt lgkmcnt(4)
	v_mfma_f32_32x32x16_bf16 v[34:49], v[148:151], v[124:127], v[34:49]
	v_mfma_f32_32x32x16_bf16 v[18:33], v[132:135], v[140:143], v[18:33]
	v_mfma_f32_32x32x16_bf16 v[2:17], v[148:151], v[140:143], v[2:17]
	ds_read_b128 v[124:127], v114 offset:96
	ds_read_b128 v[132:135], v114 offset:4704
	ds_read_b128 v[140:143], v115 offset:18528
	ds_read_b128 v[148:151], v115 offset:23136
	s_waitcnt lgkmcnt(5)
	v_mfma_f32_32x32x16_bf16 v[50:65], v[136:139], v[120:123], v[50:65]
	s_waitcnt lgkmcnt(0)
	s_barrier
; template <int AMODE, bool SWAP>
; DI void gemm_core(const u16* __restrict__ A, int lda, const u16* __restrict__ Bt, int ldb, int K, int m0, int n0, int acol,
;                   f32x16 (&acc)[2][2], u16* sA, u16* sB) {
;     ...
;   auto compute = [&]() {
;     bf16x8 a0[2], b0[2], a1[2], b1[2];
;     ldfrag(0, a0, b0);
;     ldfrag(1, a1, b1);
;     __builtin_amdgcn_sched_barrier(0);
;     mm(a0, b0);
;     __builtin_amdgcn_sched_barrier(0);
;     ldfrag(2, a0, b0);
;     __builtin_amdgcn_sched_barrier(0);
;     mm(a1, b1);
;     __builtin_amdgcn_sched_barrier(0);
;     ldfrag(3, a1, b1);
;     __builtin_amdgcn_sched_barrier(0);
;     mm(a0, b0);
;     mm(a1, b1);
;   };
;   gload(0, ra[0], rb[0]);
;   for (int kt = 0; kt < nk; ++kt) {
;     stage(ra[0], rb[0]);
;     __syncthreads();
;     if (kt + 1 < nk) gload(kt + 1, ra[0], rb[0]);
;     __builtin_amdgcn_sched_barrier(0);
;     compute();
;     __syncthreads();
;   }
; __global__ void __launch_bounds__(512, 2) mega(Params P) {
;     ...
;           const float* bgp = P.b_pg + L * DM;
;           EPI_LOOP_BEGIN EPI_SWAP_IDX
;             f32x4 bb = *reinterpret_cast<const f32x4*>(bgp + nb);
	v_mfma_f32_32x32x16_bf16 v[34:49], v[144:147], v[120:123], v[34:49]
	v_mfma_f32_32x32x16_bf16 v[18:33], v[136:139], v[128:131], v[18:33]
	v_mfma_f32_32x32x16_bf16 v[2:17], v[144:147], v[128:131], v[2:17]
	v_mfma_f32_32x32x16_bf16 v[50:65], v[140:143], v[124:127], v[50:65]
	v_mfma_f32_32x32x16_bf16 v[34:49], v[148:151], v[124:127], v[34:49]
	v_mfma_f32_32x32x16_bf16 v[18:33], v[140:143], v[132:135], v[18:33]
	v_mfma_f32_32x32x16_bf16 v[2:17], v[148:151], v[132:135], v[2:17]
	s_waitcnt vmcnt(0)
	ds_write_b128 v119, v[202:205]
	ds_write_b128 v119, v[206:209] offset:18432
	ds_write_b128 v118, v[210:213]
	ds_write_b128 v118, v[214:217] offset:18432
	ds_write_b128 v117, v[218:221]
	ds_write_b128 v117, v[222:225] offset:18432
	ds_write_b128 v116, v[152:155]
	ds_write_b128 v116, v[160:163] offset:18432
	ds_read_b128 v[120:123], v174
	ds_read_b128 v[124:127], v174 offset:32
	ds_read_b128 v[128:131], v175 offset:18432
	ds_read_b128 v[132:135], v175 offset:18464
	ds_read_b128 v[136:139], v174 offset:4608
	ds_read_b128 v[140:143], v174 offset:4640
	ds_read_b128 v[144:147], v175 offset:23040
	ds_read_b128 v[148:151], v175 offset:23072
	s_waitcnt lgkmcnt(5)
	v_mfma_f32_32x32x16_bf16 v[50:65], v[128:131], v[120:123], v[50:65]
	s_waitcnt lgkmcnt(1)
	v_mfma_f32_32x32x16_bf16 v[34:49], v[144:147], v[120:123], v[34:49]
	v_mfma_f32_32x32x16_bf16 v[18:33], v[128:131], v[136:139], v[18:33]
	v_mfma_f32_32x32x16_bf16 v[2:17], v[144:147], v[136:139], v[2:17]
	ds_read_b128 v[120:123], v174 offset:64
	ds_read_b128 v[128:131], v174 offset:4672
	ds_read_b128 v[136:139], v175 offset:18496
	ds_read_b128 v[144:147], v175 offset:23104
	v_mfma_f32_32x32x16_bf16 v[50:65], v[132:135], v[124:127], v[50:65]
	s_waitcnt lgkmcnt(4)
	v_mfma_f32_32x32x16_bf16 v[34:49], v[148:151], v[124:127], v[34:49]
	v_mfma_f32_32x32x16_bf16 v[18:33], v[132:135], v[140:143], v[18:33]
	v_mfma_f32_32x32x16_bf16 v[2:17], v[148:151], v[140:143], v[2:17]
	ds_read_b128 v[124:127], v174 offset:96
	ds_read_b128 v[132:135], v174 offset:4704
	ds_read_b128 v[140:143], v175 offset:18528
	ds_read_b128 v[148:151], v175 offset:23136
	s_waitcnt lgkmcnt(5)
	v_mfma_f32_32x32x16_bf16 v[50:65], v[136:139], v[120:123], v[50:65]
	s_waitcnt lgkmcnt(0)
	s_barrier
	v_mfma_f32_32x32x16_bf16 v[34:49], v[144:147], v[120:123], v[34:49]
	v_mfma_f32_32x32x16_bf16 v[18:33], v[136:139], v[128:131], v[18:33]
	v_mfma_f32_32x32x16_bf16 v[2:17], v[144:147], v[128:131], v[2:17]
	v_mfma_f32_32x32x16_bf16 v[50:65], v[140:143], v[124:127], v[50:65]
	v_mfma_f32_32x32x16_bf16 v[34:49], v[148:151], v[124:127], v[34:49]
	v_mfma_f32_32x32x16_bf16 v[18:33], v[140:143], v[132:135], v[18:33]
	v_mfma_f32_32x32x16_bf16 v[2:17], v[148:151], v[132:135], v[2:17]
	ds_read_b128 v[66:69], v114
	ds_read_b128 v[70:73], v114 offset:32
	ds_read_b128 v[74:77], v115 offset:18432
	ds_read_b128 v[78:81], v115 offset:18464
	ds_read_b128 v[82:85], v114 offset:4608
	ds_read_b128 v[86:89], v114 offset:4640
	ds_read_b128 v[90:93], v115 offset:23040
	ds_read_b128 v[94:97], v115 offset:23072
	s_waitcnt lgkmcnt(5)
	v_mfma_f32_32x32x16_bf16 v[50:65], v[74:77], v[66:69], v[50:65]
	s_waitcnt lgkmcnt(1)
	v_mfma_f32_32x32x16_bf16 v[34:49], v[90:93], v[66:69], v[34:49]
	v_mfma_f32_32x32x16_bf16 v[18:33], v[74:77], v[82:85], v[18:33]
	v_mfma_f32_32x32x16_bf16 v[2:17], v[90:93], v[82:85], v[2:17]
	ds_read_b128 v[66:69], v114 offset:64
	ds_read_b128 v[74:77], v114 offset:4672
	ds_read_b128 v[82:85], v115 offset:18496
	ds_read_b128 v[90:93], v115 offset:23104
	v_mfma_f32_32x32x16_bf16 v[50:65], v[78:81], v[70:73], v[50:65]
	s_waitcnt lgkmcnt(4)
	v_mfma_f32_32x32x16_bf16 v[34:49], v[94:97], v[70:73], v[34:49]
	v_mfma_f32_32x32x16_bf16 v[18:33], v[78:81], v[86:89], v[18:33]
	v_mfma_f32_32x32x16_bf16 v[2:17], v[94:97], v[86:89], v[2:17]
	ds_read_b128 v[70:73], v114 offset:96
	ds_read_b128 v[78:81], v114 offset:4704
	ds_read_b128 v[86:89], v115 offset:18528
	ds_read_b128 v[94:97], v115 offset:23136
	s_waitcnt lgkmcnt(5)
	v_mfma_f32_32x32x16_bf16 v[50:65], v[82:85], v[66:69], v[50:65]
	v_mov_b32_e32 v0, v159
	s_waitcnt lgkmcnt(0)
	s_barrier
	v_readlane_b32 s12, v252, 50
	v_lshrrev_b32_e32 v0, 3, v0
	v_mfma_f32_32x32x16_bf16 v[34:49], v[90:93], v[66:69], v[34:49]
	v_mov_b32_e32 v66, v159
	v_and_b32_e32 v0, 4, v0
	v_and_b32_e32 v66, 64, v66
	v_or3_b32 v66, v66, v0, s21
	v_ashrrev_i32_e32 v67, 31, v66
	v_readlane_b32 s13, v252, 51
	v_mfma_f32_32x32x16_bf16 v[50:65], v[86:89], v[70:73], v[50:65]
	v_mfma_f32_32x32x16_bf16 v[34:49], v[94:97], v[70:73], v[34:49]
	v_lshl_add_u64 v[70:71], v[66:67], 2, s[26:27]
	global_load_dwordx4 v[66:69], v[70:71], off
	global_load_dwordx4 v[202:205], v[70:71], off offset:32
	global_load_dwordx4 v[206:209], v[70:71], off offset:64
	global_load_dwordx4 v[210:213], v[70:71], off offset:96
	global_load_dwordx4 v[214:217], v[70:71], off offset:128
	global_load_dwordx4 v[218:221], v[70:71], off offset:160
	global_load_dwordx4 v[222:225], v[70:71], off offset:192
	global_load_dwordx4 v[152:155], v[70:71], off offset:224
	s_waitcnt vmcnt(0)
; DI float sigmoidf_(float x) { return 1.f / (1.f + __expf(-x)); }
; __global__ void __launch_bounds__(512, 2) mega(Params P) {
;     ...
;           EPI_LOOP_BEGIN EPI_SWAP_IDX
;             f32x4 bb = *reinterpret_cast<const f32x4*>(bgp + nb);
;             (void)m;
;             gatepk[mt][nt][2 * g] = pack2(sigmoidf_(acc[mt][nt][4 * g] + bb[0]), sigmoidf_(acc[mt][nt][4 * g + 1] + bb[1]));
;             gatepk[mt][nt][2 * g + 1] = pack2(sigmoidf_(acc[mt][nt][4 * g + 2] + bb[2]), sigmoidf_(acc[mt][nt][4 * g + 3] + bb[3]));
;           EPI_LOOP_END
	s_nop 7
	v_add_f32_e32 v0, v66, v50
	v_mul_f32_e32 v0, 0xbfb8aa3b, v0
	v_exp_f32_e32 v50, v0
	v_add_f32_e32 v0, v67, v51
	v_mul_f32_e32 v0, 0xbfb8aa3b, v0
	v_exp_f32_e32 v51, v0
	v_mfma_f32_32x32x16_bf16 v[18:33], v[82:85], v[74:77], v[18:33]
	v_add_f32_e64 v50, v50, 1.0
	v_add_f32_e64 v51, v51, 1.0
	v_div_scale_f32 v0, s[10:11], v51, v51, 1.0
	v_rcp_f32_e32 v72, v0
	v_mfma_f32_32x32x16_bf16 v[2:17], v[90:93], v[74:77], v[2:17]
	v_fma_f32 v73, -v0, v72, 1.0
	v_fmac_f32_e32 v72, v73, v72
	v_div_scale_f32 v73, vcc, 1.0, v51, 1.0
	v_mul_f32_e32 v74, v73, v72
	v_fma_f32 v75, -v0, v74, v73
	v_fmac_f32_e32 v74, v75, v72
	v_fma_f32 v0, -v0, v74, v73
	v_div_fmas_f32 v0, v0, v72, v74
	v_div_fixup_f32 v0, v0, v51, 1.0
	v_div_scale_f32 v51, s[10:11], v50, v50, 1.0
	v_rcp_f32_e32 v72, v51
	v_mfma_f32_32x32x16_bf16 v[18:33], v[86:89], v[78:81], v[18:33]
	v_fma_f32 v73, -v51, v72, 1.0
	v_fmac_f32_e32 v72, v73, v72
	v_div_scale_f32 v73, vcc, 1.0, v50, 1.0
	v_mul_f32_e32 v74, v73, v72
	v_fma_f32 v75, -v51, v74, v73
	v_fmac_f32_e32 v74, v75, v72
	v_fma_f32 v51, -v51, v74, v73
	v_div_fmas_f32 v51, v51, v72, v74
	v_div_fixup_f32 v50, v51, v50, 1.0
	v_cvt_pk_bf16_f32 v114, v50, v0
	v_add_f32_e32 v0, v68, v52
	v_mul_f32_e32 v0, 0xbfb8aa3b, v0
	v_exp_f32_e32 v50, v0
	v_add_f32_e32 v0, v69, v53
	v_mul_f32_e32 v0, 0xbfb8aa3b, v0
	v_exp_f32_e32 v51, v0
	v_mfma_f32_32x32x16_bf16 v[2:17], v[94:97], v[78:81], v[2:17]
	v_add_f32_e64 v50, v50, 1.0
	v_add_f32_e64 v51, v51, 1.0
	v_div_scale_f32 v0, s[10:11], v51, v51, 1.0
	v_rcp_f32_e32 v52, v0
	s_nop 0
	v_fma_f32 v53, -v0, v52, 1.0
	v_fmac_f32_e32 v52, v53, v52
	v_div_scale_f32 v53, vcc, 1.0, v51, 1.0
	v_mul_f32_e32 v72, v53, v52
	v_fma_f32 v73, -v0, v72, v53
	v_fmac_f32_e32 v72, v73, v52
	v_fma_f32 v0, -v0, v72, v53
	v_div_fmas_f32 v0, v0, v52, v72
	v_div_fixup_f32 v0, v0, v51, 1.0
	v_div_scale_f32 v51, s[10:11], v50, v50, 1.0
	v_rcp_f32_e32 v52, v51
	s_nop 0
	v_fma_f32 v53, -v51, v52, 1.0
	v_fmac_f32_e32 v52, v53, v52
	v_div_scale_f32 v53, vcc, 1.0, v50, 1.0
	v_mul_f32_e32 v72, v53, v52
	v_fma_f32 v73, -v51, v72, v53
	v_fmac_f32_e32 v72, v73, v52
	v_fma_f32 v51, -v51, v72, v53
	v_div_fmas_f32 v51, v51, v52, v72
	v_div_fixup_f32 v50, v51, v50, 1.0
	v_cvt_pk_bf16_f32 v115, v50, v0
	v_mov_b64_e32 v[50:51], v[202:203]
	v_mov_b64_e32 v[52:53], v[204:205]
	v_add_f32_e32 v0, v50, v54
	v_mul_f32_e32 v0, 0xbfb8aa3b, v0
	v_exp_f32_e32 v54, v0
	v_add_f32_e32 v0, v51, v55
	v_mul_f32_e32 v0, 0xbfb8aa3b, v0
	v_exp_f32_e32 v55, v0
	s_nop 0
	v_pk_add_f32 v[54:55], v[54:55], 1.0 op_sel_hi:[1,0]
	s_nop 0
	v_div_scale_f32 v0, s[10:11], v55, v55, 1.0
	v_rcp_f32_e32 v72, v0
	s_nop 0
	v_fma_f32 v73, -v0, v72, 1.0
	v_fmac_f32_e32 v72, v73, v72
	v_div_scale_f32 v73, vcc, 1.0, v55, 1.0
	v_mul_f32_e32 v74, v73, v72
	v_fma_f32 v75, -v0, v74, v73
	v_fmac_f32_e32 v74, v75, v72
	v_fma_f32 v0, -v0, v74, v73
	v_div_fmas_f32 v0, v0, v72, v74
	v_div_fixup_f32 v0, v0, v55, 1.0
	v_div_scale_f32 v55, s[10:11], v54, v54, 1.0
	v_rcp_f32_e32 v72, v55
	s_nop 0
	v_fma_f32 v73, -v55, v72, 1.0
	v_fmac_f32_e32 v72, v73, v72
	v_div_scale_f32 v73, vcc, 1.0, v54, 1.0
	v_mul_f32_e32 v74, v73, v72
	v_fma_f32 v75, -v55, v74, v73
	v_fmac_f32_e32 v74, v75, v72
	v_fma_f32 v55, -v55, v74, v73
	v_div_fmas_f32 v55, v55, v72, v74
	v_div_fixup_f32 v54, v55, v54, 1.0
	v_cvt_pk_bf16_f32 v116, v54, v0
	v_add_f32_e32 v0, v52, v56
	v_mul_f32_e32 v0, 0xbfb8aa3b, v0
	v_exp_f32_e32 v54, v0
	v_add_f32_e32 v0, v53, v57
	v_mul_f32_e32 v0, 0xbfb8aa3b, v0
	v_exp_f32_e32 v55, v0
	s_nop 0
	v_pk_add_f32 v[54:55], v[54:55], 1.0 op_sel_hi:[1,0]
	s_nop 0
	v_div_scale_f32 v0, s[10:11], v55, v55, 1.0
	v_rcp_f32_e32 v56, v0
	s_nop 0
	v_fma_f32 v57, -v0, v56, 1.0
	v_fmac_f32_e32 v56, v57, v56
	v_div_scale_f32 v57, vcc, 1.0, v55, 1.0
	v_mul_f32_e32 v72, v57, v56
	v_fma_f32 v73, -v0, v72, v57
	v_fmac_f32_e32 v72, v73, v56
	v_fma_f32 v0, -v0, v72, v57
	v_div_fmas_f32 v0, v0, v56, v72
	v_div_fixup_f32 v0, v0, v55, 1.0
	v_div_scale_f32 v55, s[10:11], v54, v54, 1.0
	v_rcp_f32_e32 v56, v55
	s_nop 0
	v_fma_f32 v57, -v55, v56, 1.0
	v_fmac_f32_e32 v56, v57, v56
	v_div_scale_f32 v57, vcc, 1.0, v54, 1.0
	v_mul_f32_e32 v72, v57, v56
	v_fma_f32 v73, -v55, v72, v57
	v_fmac_f32_e32 v72, v73, v56
	v_fma_f32 v55, -v55, v72, v57
	v_div_fmas_f32 v55, v55, v56, v72
	v_div_fixup_f32 v54, v55, v54, 1.0
	v_cvt_pk_bf16_f32 v117, v54, v0
	v_mov_b64_e32 v[54:55], v[206:207]
	v_mov_b64_e32 v[56:57], v[208:209]
	v_add_f32_e32 v0, v54, v58
	v_mul_f32_e32 v0, 0xbfb8aa3b, v0
	v_exp_f32_e32 v58, v0
	v_add_f32_e32 v0, v55, v59
	v_mul_f32_e32 v0, 0xbfb8aa3b, v0
	v_exp_f32_e32 v59, v0
	s_nop 0
	v_pk_add_f32 v[58:59], v[58:59], 1.0 op_sel_hi:[1,0]
	s_nop 0
	v_div_scale_f32 v0, s[10:11], v59, v59, 1.0
	v_rcp_f32_e32 v72, v0
	s_nop 0
	v_fma_f32 v73, -v0, v72, 1.0
	v_fmac_f32_e32 v72, v73, v72
	v_div_scale_f32 v73, vcc, 1.0, v59, 1.0
	v_mul_f32_e32 v74, v73, v72
	v_fma_f32 v75, -v0, v74, v73
	v_fmac_f32_e32 v74, v75, v72
	v_fma_f32 v0, -v0, v74, v73
	v_div_fmas_f32 v0, v0, v72, v74
	v_div_fixup_f32 v0, v0, v59, 1.0
	v_div_scale_f32 v59, s[10:11], v58, v58, 1.0
	v_rcp_f32_e32 v72, v59
	s_nop 0
	v_fma_f32 v73, -v59, v72, 1.0
	v_fmac_f32_e32 v72, v73, v72
	v_div_scale_f32 v73, vcc, 1.0, v58, 1.0
	v_mul_f32_e32 v74, v73, v72
	v_fma_f32 v75, -v59, v74, v73
	v_fmac_f32_e32 v74, v75, v72
	v_fma_f32 v59, -v59, v74, v73
	v_div_fmas_f32 v59, v59, v72, v74
	v_div_fixup_f32 v58, v59, v58, 1.0
	v_cvt_pk_bf16_f32 v118, v58, v0
	v_add_f32_e32 v0, v56, v60
	v_mul_f32_e32 v0, 0xbfb8aa3b, v0
	v_exp_f32_e32 v58, v0
	v_add_f32_e32 v0, v57, v61
	v_mul_f32_e32 v0, 0xbfb8aa3b, v0
	v_exp_f32_e32 v59, v0
	s_nop 0
	v_pk_add_f32 v[58:59], v[58:59], 1.0 op_sel_hi:[1,0]
; DI float sigmoidf_(float x) { return 1.f / (1.f + __expf(-x)); }
; __global__ void __launch_bounds__(512, 2) mega(Params P) {
;     ...
;           EPI_LOOP_BEGIN EPI_SWAP_IDX
;             f32x4 bb = *reinterpret_cast<const f32x4*>(bgp + nb);
;             (void)m;
;             gatepk[mt][nt][2 * g] = pack2(sigmoidf_(acc[mt][nt][4 * g] + bb[0]), sigmoidf_(acc[mt][nt][4 * g + 1] + bb[1]));
;             gatepk[mt][nt][2 * g + 1] = pack2(sigmoidf_(acc[mt][nt][4 * g + 2] + bb[2]), sigmoidf_(acc[mt][nt][4 * g + 3] + bb[3]));
;           EPI_LOOP_END
	s_nop 0
	v_div_scale_f32 v0, s[10:11], v59, v59, 1.0
	v_rcp_f32_e32 v60, v0
	s_nop 0
	v_fma_f32 v61, -v0, v60, 1.0
	v_fmac_f32_e32 v60, v61, v60
	v_div_scale_f32 v61, vcc, 1.0, v59, 1.0
	v_mul_f32_e32 v72, v61, v60
	v_fma_f32 v73, -v0, v72, v61
	v_fmac_f32_e32 v72, v73, v60
	v_fma_f32 v0, -v0, v72, v61
	v_div_fmas_f32 v0, v0, v60, v72
	v_div_fixup_f32 v0, v0, v59, 1.0
	v_div_scale_f32 v59, s[10:11], v58, v58, 1.0
	v_rcp_f32_e32 v60, v59
	s_nop 0
	v_fma_f32 v61, -v59, v60, 1.0
	v_fmac_f32_e32 v60, v61, v60
	v_div_scale_f32 v61, vcc, 1.0, v58, 1.0
	v_mul_f32_e32 v72, v61, v60
	v_fma_f32 v73, -v59, v72, v61
	v_fmac_f32_e32 v72, v73, v60
	v_fma_f32 v59, -v59, v72, v61
	v_div_fmas_f32 v59, v59, v60, v72
	v_div_fixup_f32 v58, v59, v58, 1.0
	v_cvt_pk_bf16_f32 v119, v58, v0
	v_mov_b64_e32 v[58:59], v[210:211]
	v_mov_b64_e32 v[60:61], v[212:213]
	v_add_f32_e32 v0, v58, v62
	v_mul_f32_e32 v0, 0xbfb8aa3b, v0
	v_exp_f32_e32 v62, v0
	v_add_f32_e32 v0, v59, v63
	v_mul_f32_e32 v0, 0xbfb8aa3b, v0
	v_exp_f32_e32 v63, v0
	s_nop 0
	v_pk_add_f32 v[62:63], v[62:63], 1.0 op_sel_hi:[1,0]
	s_nop 0
	v_div_scale_f32 v0, s[10:11], v63, v63, 1.0
	v_rcp_f32_e32 v72, v0
	s_nop 0
	v_fma_f32 v73, -v0, v72, 1.0
	v_fmac_f32_e32 v72, v73, v72
	v_div_scale_f32 v73, vcc, 1.0, v63, 1.0
	v_mul_f32_e32 v74, v73, v72
	v_fma_f32 v75, -v0, v74, v73
	v_fmac_f32_e32 v74, v75, v72
	v_fma_f32 v0, -v0, v74, v73
	v_div_fmas_f32 v0, v0, v72, v74
	v_div_fixup_f32 v0, v0, v63, 1.0
	v_div_scale_f32 v63, s[10:11], v62, v62, 1.0
	v_rcp_f32_e32 v72, v63
	s_nop 0
	v_fma_f32 v73, -v63, v72, 1.0
	v_fmac_f32_e32 v72, v73, v72
	v_div_scale_f32 v73, vcc, 1.0, v62, 1.0
	v_mul_f32_e32 v74, v73, v72
	v_fma_f32 v75, -v63, v74, v73
	v_fmac_f32_e32 v74, v75, v72
	v_fma_f32 v63, -v63, v74, v73
	v_div_fmas_f32 v63, v63, v72, v74
	v_div_fixup_f32 v62, v63, v62, 1.0
	v_cvt_pk_bf16_f32 v120, v62, v0
	v_add_f32_e32 v0, v60, v64
	v_mul_f32_e32 v0, 0xbfb8aa3b, v0
	v_exp_f32_e32 v62, v0
	v_add_f32_e32 v0, v61, v65
	v_mul_f32_e32 v0, 0xbfb8aa3b, v0
	v_exp_f32_e32 v63, v0
	s_nop 0
	v_pk_add_f32 v[62:63], v[62:63], 1.0 op_sel_hi:[1,0]
	s_nop 0
	v_div_scale_f32 v0, s[10:11], v63, v63, 1.0
	v_rcp_f32_e32 v64, v0
	s_nop 0
	v_fma_f32 v65, -v0, v64, 1.0
	v_fmac_f32_e32 v64, v65, v64
	v_div_scale_f32 v65, vcc, 1.0, v63, 1.0
	v_mul_f32_e32 v72, v65, v64
	v_fma_f32 v73, -v0, v72, v65
	v_fmac_f32_e32 v72, v73, v64
	v_fma_f32 v0, -v0, v72, v65
	v_div_fmas_f32 v0, v0, v64, v72
	v_div_fixup_f32 v0, v0, v63, 1.0
	v_div_scale_f32 v63, s[10:11], v62, v62, 1.0
	v_rcp_f32_e32 v64, v63
	s_nop 0
	v_fma_f32 v65, -v63, v64, 1.0
	v_fmac_f32_e32 v64, v65, v64
	v_div_scale_f32 v65, vcc, 1.0, v62, 1.0
	v_mul_f32_e32 v72, v65, v64
	v_fma_f32 v73, -v63, v72, v65
	v_fmac_f32_e32 v72, v73, v64
	v_fma_f32 v63, -v63, v72, v65
	v_div_fmas_f32 v63, v63, v64, v72
	v_div_fixup_f32 v62, v63, v62, 1.0
	v_cvt_pk_bf16_f32 v121, v62, v0
	v_mov_b64_e32 v[62:63], v[214:215]
	v_mov_b64_e32 v[64:65], v[216:217]
	v_add_f32_e32 v0, v62, v34
	v_mul_f32_e32 v0, 0xbfb8aa3b, v0
	v_exp_f32_e32 v34, v0
	v_add_f32_e32 v0, v63, v35
	v_mul_f32_e32 v0, 0xbfb8aa3b, v0
	v_exp_f32_e32 v35, v0
	s_nop 0
	v_pk_add_f32 v[34:35], v[34:35], 1.0 op_sel_hi:[1,0]
	s_nop 0
	v_div_scale_f32 v0, s[10:11], v35, v35, 1.0
	v_rcp_f32_e32 v72, v0
	s_nop 0
	v_fma_f32 v73, -v0, v72, 1.0
	v_fmac_f32_e32 v72, v73, v72
	v_div_scale_f32 v73, vcc, 1.0, v35, 1.0
	v_mul_f32_e32 v74, v73, v72
	v_fma_f32 v75, -v0, v74, v73
	v_fmac_f32_e32 v74, v75, v72
	v_fma_f32 v0, -v0, v74, v73
	v_div_fmas_f32 v0, v0, v72, v74
	v_div_fixup_f32 v0, v0, v35, 1.0
	v_div_scale_f32 v35, s[10:11], v34, v34, 1.0
	v_rcp_f32_e32 v72, v35
	s_nop 0
	v_fma_f32 v73, -v35, v72, 1.0
	v_fmac_f32_e32 v72, v73, v72
	v_div_scale_f32 v73, vcc, 1.0, v34, 1.0
	v_mul_f32_e32 v74, v73, v72
	v_fma_f32 v75, -v35, v74, v73
	v_fmac_f32_e32 v74, v75, v72
	v_fma_f32 v35, -v35, v74, v73
	v_div_fmas_f32 v35, v35, v72, v74
	v_div_fixup_f32 v34, v35, v34, 1.0
	v_cvt_pk_bf16_f32 v122, v34, v0
	v_add_f32_e32 v0, v64, v36
	v_mul_f32_e32 v0, 0xbfb8aa3b, v0
	v_exp_f32_e32 v34, v0
	v_add_f32_e32 v0, v65, v37
	v_mul_f32_e32 v0, 0xbfb8aa3b, v0
	v_exp_f32_e32 v35, v0
	s_nop 0
	v_pk_add_f32 v[34:35], v[34:35], 1.0 op_sel_hi:[1,0]
	s_nop 0
	v_div_scale_f32 v0, s[10:11], v35, v35, 1.0
	v_rcp_f32_e32 v36, v0
	s_nop 0
	v_fma_f32 v37, -v0, v36, 1.0
	v_fmac_f32_e32 v36, v37, v36
	v_div_scale_f32 v37, vcc, 1.0, v35, 1.0
	v_mul_f32_e32 v72, v37, v36
	v_fma_f32 v73, -v0, v72, v37
	v_fmac_f32_e32 v72, v73, v36
	v_fma_f32 v0, -v0, v72, v37
	v_div_fmas_f32 v0, v0, v36, v72
	v_div_fixup_f32 v0, v0, v35, 1.0
	v_div_scale_f32 v35, s[10:11], v34, v34, 1.0
	v_rcp_f32_e32 v36, v35
	s_nop 0
	v_fma_f32 v37, -v35, v36, 1.0
	v_fmac_f32_e32 v36, v37, v36
	v_div_scale_f32 v37, vcc, 1.0, v34, 1.0
	v_mul_f32_e32 v72, v37, v36
	v_fma_f32 v73, -v35, v72, v37
	v_fmac_f32_e32 v72, v73, v36
	v_fma_f32 v35, -v35, v72, v37
	v_div_fmas_f32 v35, v35, v36, v72
	v_div_fixup_f32 v34, v35, v34, 1.0
	v_cvt_pk_bf16_f32 v123, v34, v0
	v_mov_b64_e32 v[34:35], v[218:219]
	v_mov_b64_e32 v[36:37], v[220:221]
	v_add_f32_e32 v0, v34, v38
	v_mul_f32_e32 v0, 0xbfb8aa3b, v0
	v_exp_f32_e32 v38, v0
	v_add_f32_e32 v0, v35, v39
	v_mul_f32_e32 v0, 0xbfb8aa3b, v0
	v_exp_f32_e32 v39, v0
	s_nop 0
	v_pk_add_f32 v[38:39], v[38:39], 1.0 op_sel_hi:[1,0]
	s_nop 0
	v_div_scale_f32 v0, s[10:11], v39, v39, 1.0
	v_rcp_f32_e32 v72, v0
	s_nop 0
	v_fma_f32 v73, -v0, v72, 1.0
	v_fmac_f32_e32 v72, v73, v72
	v_div_scale_f32 v73, vcc, 1.0, v39, 1.0
	v_mul_f32_e32 v74, v73, v72
	v_fma_f32 v75, -v0, v74, v73
	v_fmac_f32_e32 v74, v75, v72
	v_fma_f32 v0, -v0, v74, v73
	v_div_fmas_f32 v0, v0, v72, v74
	v_div_fixup_f32 v0, v0, v39, 1.0
; DI float sigmoidf_(float x) { return 1.f / (1.f + __expf(-x)); }
; __global__ void __launch_bounds__(512, 2) mega(Params P) {
;     ...
;           EPI_LOOP_BEGIN EPI_SWAP_IDX
;             f32x4 bb = *reinterpret_cast<const f32x4*>(bgp + nb);
;             (void)m;
;             gatepk[mt][nt][2 * g] = pack2(sigmoidf_(acc[mt][nt][4 * g] + bb[0]), sigmoidf_(acc[mt][nt][4 * g + 1] + bb[1]));
;             gatepk[mt][nt][2 * g + 1] = pack2(sigmoidf_(acc[mt][nt][4 * g + 2] + bb[2]), sigmoidf_(acc[mt][nt][4 * g + 3] + bb[3]));
;           EPI_LOOP_END
	v_div_scale_f32 v39, s[10:11], v38, v38, 1.0
	v_rcp_f32_e32 v72, v39
	s_nop 0
	v_fma_f32 v73, -v39, v72, 1.0
	v_fmac_f32_e32 v72, v73, v72
	v_div_scale_f32 v73, vcc, 1.0, v38, 1.0
	v_mul_f32_e32 v74, v73, v72
	v_fma_f32 v75, -v39, v74, v73
	v_fmac_f32_e32 v74, v75, v72
	v_fma_f32 v39, -v39, v74, v73
	v_div_fmas_f32 v39, v39, v72, v74
	v_div_fixup_f32 v38, v39, v38, 1.0
	v_cvt_pk_bf16_f32 v124, v38, v0
	v_add_f32_e32 v0, v36, v40
	v_mul_f32_e32 v0, 0xbfb8aa3b, v0
	v_exp_f32_e32 v38, v0
	v_add_f32_e32 v0, v37, v41
	v_mul_f32_e32 v0, 0xbfb8aa3b, v0
	v_exp_f32_e32 v39, v0
	s_nop 0
	v_pk_add_f32 v[38:39], v[38:39], 1.0 op_sel_hi:[1,0]
	s_nop 0
	v_div_scale_f32 v0, s[10:11], v39, v39, 1.0
	v_rcp_f32_e32 v40, v0
	s_nop 0
	v_fma_f32 v41, -v0, v40, 1.0
	v_fmac_f32_e32 v40, v41, v40
	v_div_scale_f32 v41, vcc, 1.0, v39, 1.0
	v_mul_f32_e32 v72, v41, v40
	v_fma_f32 v73, -v0, v72, v41
	v_fmac_f32_e32 v72, v73, v40
	v_fma_f32 v0, -v0, v72, v41
	v_div_fmas_f32 v0, v0, v40, v72
	v_div_fixup_f32 v0, v0, v39, 1.0
	v_div_scale_f32 v39, s[10:11], v38, v38, 1.0
	v_rcp_f32_e32 v40, v39
	s_nop 0
	v_fma_f32 v41, -v39, v40, 1.0
	v_fmac_f32_e32 v40, v41, v40
	v_div_scale_f32 v41, vcc, 1.0, v38, 1.0
	v_mul_f32_e32 v72, v41, v40
	v_fma_f32 v73, -v39, v72, v41
	v_fmac_f32_e32 v72, v73, v40
	v_fma_f32 v39, -v39, v72, v41
	v_div_fmas_f32 v39, v39, v40, v72
	v_div_fixup_f32 v38, v39, v38, 1.0
	v_cvt_pk_bf16_f32 v125, v38, v0
	v_mov_b64_e32 v[38:39], v[222:223]
	v_mov_b64_e32 v[40:41], v[224:225]
	v_add_f32_e32 v0, v38, v42
	v_mul_f32_e32 v0, 0xbfb8aa3b, v0
	v_exp_f32_e32 v42, v0
	v_add_f32_e32 v0, v39, v43
	v_mul_f32_e32 v0, 0xbfb8aa3b, v0
	v_exp_f32_e32 v43, v0
	s_nop 0
	v_pk_add_f32 v[42:43], v[42:43], 1.0 op_sel_hi:[1,0]
	s_nop 0
	v_div_scale_f32 v0, s[10:11], v43, v43, 1.0
	v_rcp_f32_e32 v72, v0
	s_nop 0
	v_fma_f32 v73, -v0, v72, 1.0
	v_fmac_f32_e32 v72, v73, v72
	v_div_scale_f32 v73, vcc, 1.0, v43, 1.0
	v_mul_f32_e32 v74, v73, v72
	v_fma_f32 v75, -v0, v74, v73
	v_fmac_f32_e32 v74, v75, v72
	v_fma_f32 v0, -v0, v74, v73
	v_div_fmas_f32 v0, v0, v72, v74
	v_div_fixup_f32 v0, v0, v43, 1.0
	v_div_scale_f32 v43, s[10:11], v42, v42, 1.0
	v_rcp_f32_e32 v72, v43
	s_nop 0
	v_fma_f32 v73, -v43, v72, 1.0
	v_fmac_f32_e32 v72, v73, v72
	v_div_scale_f32 v73, vcc, 1.0, v42, 1.0
	v_mul_f32_e32 v74, v73, v72
	v_fma_f32 v75, -v43, v74, v73
	v_fmac_f32_e32 v74, v75, v72
	v_fma_f32 v43, -v43, v74, v73
	v_div_fmas_f32 v43, v43, v72, v74
	v_div_fixup_f32 v42, v43, v42, 1.0
	v_cvt_pk_bf16_f32 v126, v42, v0
	v_add_f32_e32 v0, v40, v44
	v_mul_f32_e32 v0, 0xbfb8aa3b, v0
	v_exp_f32_e32 v42, v0
	v_add_f32_e32 v0, v41, v45
	v_mul_f32_e32 v0, 0xbfb8aa3b, v0
	v_exp_f32_e32 v43, v0
	s_nop 0
	v_pk_add_f32 v[42:43], v[42:43], 1.0 op_sel_hi:[1,0]
	s_nop 0
	v_div_scale_f32 v0, s[10:11], v43, v43, 1.0
	v_rcp_f32_e32 v44, v0
	s_nop 0
	v_fma_f32 v45, -v0, v44, 1.0
	v_fmac_f32_e32 v44, v45, v44
	v_div_scale_f32 v45, vcc, 1.0, v43, 1.0
	v_mul_f32_e32 v72, v45, v44
	v_fma_f32 v73, -v0, v72, v45
	v_fmac_f32_e32 v72, v73, v44
	v_fma_f32 v0, -v0, v72, v45
	v_div_fmas_f32 v0, v0, v44, v72
	v_div_fixup_f32 v0, v0, v43, 1.0
	v_div_scale_f32 v43, s[10:11], v42, v42, 1.0
	v_rcp_f32_e32 v44, v43
	s_nop 0
	v_fma_f32 v45, -v43, v44, 1.0
	v_fmac_f32_e32 v44, v45, v44
	v_div_scale_f32 v45, vcc, 1.0, v42, 1.0
	v_mul_f32_e32 v72, v45, v44
	v_fma_f32 v73, -v43, v72, v45
	v_fmac_f32_e32 v72, v73, v44
	v_fma_f32 v43, -v43, v72, v45
	v_div_fmas_f32 v43, v43, v44, v72
	v_div_fixup_f32 v42, v43, v42, 1.0
	v_cvt_pk_bf16_f32 v127, v42, v0
	v_mov_b64_e32 v[42:43], v[152:153]
	v_mov_b64_e32 v[44:45], v[154:155]
	v_add_f32_e32 v0, v42, v46
	v_mul_f32_e32 v0, 0xbfb8aa3b, v0
	v_exp_f32_e32 v46, v0
	v_add_f32_e32 v0, v43, v47
	v_mul_f32_e32 v0, 0xbfb8aa3b, v0
	v_exp_f32_e32 v47, v0
	s_nop 0
	v_pk_add_f32 v[46:47], v[46:47], 1.0 op_sel_hi:[1,0]
	s_nop 0
	v_div_scale_f32 v0, s[10:11], v47, v47, 1.0
	v_rcp_f32_e32 v70, v0
	s_nop 0
	v_fma_f32 v71, -v0, v70, 1.0
	v_fmac_f32_e32 v70, v71, v70
	v_div_scale_f32 v71, vcc, 1.0, v47, 1.0
	v_mul_f32_e32 v72, v71, v70
	v_fma_f32 v73, -v0, v72, v71
	v_fmac_f32_e32 v72, v73, v70
	v_fma_f32 v0, -v0, v72, v71
	v_div_fmas_f32 v0, v0, v70, v72
	v_div_fixup_f32 v0, v0, v47, 1.0
	v_div_scale_f32 v47, s[10:11], v46, v46, 1.0
	v_rcp_f32_e32 v70, v47
	s_nop 0
	v_fma_f32 v71, -v47, v70, 1.0
	v_fmac_f32_e32 v70, v71, v70
	v_div_scale_f32 v71, vcc, 1.0, v46, 1.0
	v_mul_f32_e32 v72, v71, v70
	v_fma_f32 v73, -v47, v72, v71
	v_fmac_f32_e32 v72, v73, v70
	v_fma_f32 v47, -v47, v72, v71
	v_div_fmas_f32 v47, v47, v70, v72
	v_div_fixup_f32 v46, v47, v46, 1.0
	v_cvt_pk_bf16_f32 v128, v46, v0
	v_add_f32_e32 v0, v44, v48
	v_mul_f32_e32 v0, 0xbfb8aa3b, v0
	v_exp_f32_e32 v46, v0
	v_add_f32_e32 v0, v45, v49
	v_mul_f32_e32 v0, 0xbfb8aa3b, v0
	v_exp_f32_e32 v47, v0
	s_nop 0
	v_pk_add_f32 v[46:47], v[46:47], 1.0 op_sel_hi:[1,0]
	s_nop 0
	v_div_scale_f32 v0, s[10:11], v47, v47, 1.0
	v_rcp_f32_e32 v48, v0
	s_nop 0
	v_fma_f32 v49, -v0, v48, 1.0
	v_fmac_f32_e32 v48, v49, v48
	v_div_scale_f32 v49, vcc, 1.0, v47, 1.0
	v_mul_f32_e32 v70, v49, v48
	v_fma_f32 v71, -v0, v70, v49
	v_fmac_f32_e32 v70, v71, v48
	v_fma_f32 v0, -v0, v70, v49
	v_div_fmas_f32 v0, v0, v48, v70
	v_div_fixup_f32 v0, v0, v47, 1.0
	v_div_scale_f32 v47, s[10:11], v46, v46, 1.0
	v_rcp_f32_e32 v48, v47
	s_nop 0
	v_fma_f32 v49, -v47, v48, 1.0
	v_fmac_f32_e32 v48, v49, v48
	v_div_scale_f32 v49, vcc, 1.0, v46, 1.0
	v_mul_f32_e32 v70, v49, v48
	v_fma_f32 v71, -v47, v70, v49
	v_fmac_f32_e32 v70, v71, v48
	v_fma_f32 v47, -v47, v70, v49
	v_div_fmas_f32 v47, v47, v48, v70
	v_div_fixup_f32 v46, v47, v46, 1.0
	v_cvt_pk_bf16_f32 v129, v46, v0
	v_add_f32_e32 v0, v66, v18
; DI float sigmoidf_(float x) { return 1.f / (1.f + __expf(-x)); }
; __global__ void __launch_bounds__(512, 2) mega(Params P) {
;     ...
;           EPI_LOOP_BEGIN EPI_SWAP_IDX
;             f32x4 bb = *reinterpret_cast<const f32x4*>(bgp + nb);
;             (void)m;
;             gatepk[mt][nt][2 * g] = pack2(sigmoidf_(acc[mt][nt][4 * g] + bb[0]), sigmoidf_(acc[mt][nt][4 * g + 1] + bb[1]));
;             gatepk[mt][nt][2 * g + 1] = pack2(sigmoidf_(acc[mt][nt][4 * g + 2] + bb[2]), sigmoidf_(acc[mt][nt][4 * g + 3] + bb[3]));
;           EPI_LOOP_END
	v_mul_f32_e32 v0, 0xbfb8aa3b, v0
	v_exp_f32_e32 v18, v0
	v_add_f32_e32 v0, v67, v19
	v_mul_f32_e32 v0, 0xbfb8aa3b, v0
	v_exp_f32_e32 v19, v0
	s_nop 0
	v_pk_add_f32 v[18:19], v[18:19], 1.0 op_sel_hi:[1,0]
	s_nop 0
	v_div_scale_f32 v0, s[10:11], v19, v19, 1.0
	v_rcp_f32_e32 v46, v0
	s_nop 0
	v_fma_f32 v47, -v0, v46, 1.0
	v_fmac_f32_e32 v46, v47, v46
	v_div_scale_f32 v47, vcc, 1.0, v19, 1.0
	v_mul_f32_e32 v48, v47, v46
	v_fma_f32 v49, -v0, v48, v47
	v_fmac_f32_e32 v48, v49, v46
	v_fma_f32 v0, -v0, v48, v47
	v_div_fmas_f32 v0, v0, v46, v48
	v_div_fixup_f32 v0, v0, v19, 1.0
	v_div_scale_f32 v19, s[10:11], v18, v18, 1.0
	v_rcp_f32_e32 v46, v19
	s_nop 0
	v_fma_f32 v47, -v19, v46, 1.0
	v_fmac_f32_e32 v46, v47, v46
	v_div_scale_f32 v47, vcc, 1.0, v18, 1.0
	v_mul_f32_e32 v48, v47, v46
	v_fma_f32 v49, -v19, v48, v47
	v_fmac_f32_e32 v48, v49, v46
	v_fma_f32 v19, -v19, v48, v47
	v_div_fmas_f32 v19, v19, v46, v48
	v_div_fixup_f32 v18, v19, v18, 1.0
	v_cvt_pk_bf16_f32 v130, v18, v0
	v_add_f32_e32 v0, v68, v20
	v_mul_f32_e32 v0, 0xbfb8aa3b, v0
	v_exp_f32_e32 v18, v0
	v_add_f32_e32 v0, v69, v21
	v_mul_f32_e32 v0, 0xbfb8aa3b, v0
	v_exp_f32_e32 v19, v0
	s_nop 0
	v_pk_add_f32 v[18:19], v[18:19], 1.0 op_sel_hi:[1,0]
	s_nop 0
	v_div_scale_f32 v0, s[10:11], v19, v19, 1.0
	v_rcp_f32_e32 v20, v0
	s_nop 0
	v_fma_f32 v21, -v0, v20, 1.0
	v_fmac_f32_e32 v20, v21, v20
	v_div_scale_f32 v21, vcc, 1.0, v19, 1.0
	v_mul_f32_e32 v46, v21, v20
	v_fma_f32 v47, -v0, v46, v21
	v_fmac_f32_e32 v46, v47, v20
	v_fma_f32 v0, -v0, v46, v21
	v_div_fmas_f32 v0, v0, v20, v46
	v_div_fixup_f32 v0, v0, v19, 1.0
	v_div_scale_f32 v19, s[10:11], v18, v18, 1.0
	v_rcp_f32_e32 v20, v19
	s_nop 0
	v_fma_f32 v21, -v19, v20, 1.0
	v_fmac_f32_e32 v20, v21, v20
	v_div_scale_f32 v21, vcc, 1.0, v18, 1.0
	v_mul_f32_e32 v46, v21, v20
	v_fma_f32 v47, -v19, v46, v21
	v_fmac_f32_e32 v46, v47, v20
	v_fma_f32 v19, -v19, v46, v21
	v_div_fmas_f32 v19, v19, v20, v46
	v_div_fixup_f32 v18, v19, v18, 1.0
	v_cvt_pk_bf16_f32 v131, v18, v0
	v_add_f32_e32 v0, v50, v22
	v_mul_f32_e32 v0, 0xbfb8aa3b, v0
	v_exp_f32_e32 v18, v0
	v_add_f32_e32 v0, v51, v23
	v_mul_f32_e32 v0, 0xbfb8aa3b, v0
	v_exp_f32_e32 v19, v0
	s_nop 0
	v_pk_add_f32 v[18:19], v[18:19], 1.0 op_sel_hi:[1,0]
	s_nop 0
	v_div_scale_f32 v0, s[10:11], v19, v19, 1.0
	v_rcp_f32_e32 v20, v0
	s_nop 0
	v_fma_f32 v21, -v0, v20, 1.0
	v_fmac_f32_e32 v20, v21, v20
	v_div_scale_f32 v21, vcc, 1.0, v19, 1.0
	v_mul_f32_e32 v22, v21, v20
	v_fma_f32 v23, -v0, v22, v21
	v_fmac_f32_e32 v22, v23, v20
	v_fma_f32 v0, -v0, v22, v21
	v_div_fmas_f32 v0, v0, v20, v22
	v_div_fixup_f32 v0, v0, v19, 1.0
	v_div_scale_f32 v19, s[10:11], v18, v18, 1.0
	v_rcp_f32_e32 v20, v19
	s_nop 0
	v_fma_f32 v21, -v19, v20, 1.0
	v_fmac_f32_e32 v20, v21, v20
	v_div_scale_f32 v21, vcc, 1.0, v18, 1.0
	v_mul_f32_e32 v22, v21, v20
	v_fma_f32 v23, -v19, v22, v21
	v_fmac_f32_e32 v22, v23, v20
	v_fma_f32 v19, -v19, v22, v21
	v_div_fmas_f32 v19, v19, v20, v22
	v_div_fixup_f32 v18, v19, v18, 1.0
	v_cvt_pk_bf16_f32 v132, v18, v0
	v_add_f32_e32 v0, v52, v24
	v_mul_f32_e32 v0, 0xbfb8aa3b, v0
	v_exp_f32_e32 v18, v0
	v_add_f32_e32 v0, v53, v25
	v_mul_f32_e32 v0, 0xbfb8aa3b, v0
	v_exp_f32_e32 v19, v0
	s_nop 0
	v_pk_add_f32 v[18:19], v[18:19], 1.0 op_sel_hi:[1,0]
	s_nop 0
	v_div_scale_f32 v0, s[10:11], v19, v19, 1.0
	v_rcp_f32_e32 v20, v0
	s_nop 0
	v_fma_f32 v21, -v0, v20, 1.0
	v_fmac_f32_e32 v20, v21, v20
	v_div_scale_f32 v21, vcc, 1.0, v19, 1.0
	v_mul_f32_e32 v22, v21, v20
	v_fma_f32 v23, -v0, v22, v21
	v_fmac_f32_e32 v22, v23, v20
	v_fma_f32 v0, -v0, v22, v21
	v_div_fmas_f32 v0, v0, v20, v22
	v_div_fixup_f32 v0, v0, v19, 1.0
	v_div_scale_f32 v19, s[10:11], v18, v18, 1.0
	v_rcp_f32_e32 v20, v19
	s_nop 0
	v_fma_f32 v21, -v19, v20, 1.0
	v_fmac_f32_e32 v20, v21, v20
	v_div_scale_f32 v21, vcc, 1.0, v18, 1.0
	v_mul_f32_e32 v22, v21, v20
	v_fma_f32 v23, -v19, v22, v21
	v_fmac_f32_e32 v22, v23, v20
	v_fma_f32 v19, -v19, v22, v21
	v_div_fmas_f32 v19, v19, v20, v22
	v_div_fixup_f32 v18, v19, v18, 1.0
	v_cvt_pk_bf16_f32 v133, v18, v0
	v_add_f32_e32 v0, v54, v26
	v_mul_f32_e32 v0, 0xbfb8aa3b, v0
	v_exp_f32_e32 v18, v0
	v_add_f32_e32 v0, v55, v27
	v_mul_f32_e32 v0, 0xbfb8aa3b, v0
	v_exp_f32_e32 v19, v0
	s_nop 0
	v_pk_add_f32 v[18:19], v[18:19], 1.0 op_sel_hi:[1,0]
	s_nop 0
	v_div_scale_f32 v0, s[10:11], v19, v19, 1.0
	v_rcp_f32_e32 v20, v0
	s_nop 0
	v_fma_f32 v21, -v0, v20, 1.0
	v_fmac_f32_e32 v20, v21, v20
	v_div_scale_f32 v21, vcc, 1.0, v19, 1.0
	v_mul_f32_e32 v22, v21, v20
	v_fma_f32 v23, -v0, v22, v21
	v_fmac_f32_e32 v22, v23, v20
	v_fma_f32 v0, -v0, v22, v21
	v_div_fmas_f32 v0, v0, v20, v22
	v_div_fixup_f32 v0, v0, v19, 1.0
	v_div_scale_f32 v19, s[10:11], v18, v18, 1.0
	v_rcp_f32_e32 v20, v19
	s_nop 0
	v_fma_f32 v21, -v19, v20, 1.0
	v_fmac_f32_e32 v20, v21, v20
	v_div_scale_f32 v21, vcc, 1.0, v18, 1.0
	v_mul_f32_e32 v22, v21, v20
	v_fma_f32 v23, -v19, v22, v21
	v_fmac_f32_e32 v22, v23, v20
	v_fma_f32 v19, -v19, v22, v21
	v_div_fmas_f32 v19, v19, v20, v22
	v_div_fixup_f32 v18, v19, v18, 1.0
	v_cvt_pk_bf16_f32 v134, v18, v0
	v_add_f32_e32 v0, v56, v28
	v_mul_f32_e32 v0, 0xbfb8aa3b, v0
	v_exp_f32_e32 v18, v0
	v_add_f32_e32 v0, v57, v29
	v_mul_f32_e32 v0, 0xbfb8aa3b, v0
	v_exp_f32_e32 v19, v0
	s_nop 0
	v_pk_add_f32 v[18:19], v[18:19], 1.0 op_sel_hi:[1,0]
	s_nop 0
	v_div_scale_f32 v0, s[10:11], v19, v19, 1.0
	v_rcp_f32_e32 v20, v0
	s_nop 0
	v_fma_f32 v21, -v0, v20, 1.0
	v_fmac_f32_e32 v20, v21, v20
	v_div_scale_f32 v21, vcc, 1.0, v19, 1.0
	v_mul_f32_e32 v22, v21, v20
	v_fma_f32 v23, -v0, v22, v21
	v_fmac_f32_e32 v22, v23, v20
	v_fma_f32 v0, -v0, v22, v21
	v_div_fmas_f32 v0, v0, v20, v22
	v_div_fixup_f32 v0, v0, v19, 1.0
; DI float sigmoidf_(float x) { return 1.f / (1.f + __expf(-x)); }
; __global__ void __launch_bounds__(512, 2) mega(Params P) {
;     ...
;           EPI_LOOP_BEGIN EPI_SWAP_IDX
;             f32x4 bb = *reinterpret_cast<const f32x4*>(bgp + nb);
;             (void)m;
;             gatepk[mt][nt][2 * g] = pack2(sigmoidf_(acc[mt][nt][4 * g] + bb[0]), sigmoidf_(acc[mt][nt][4 * g + 1] + bb[1]));
;             gatepk[mt][nt][2 * g + 1] = pack2(sigmoidf_(acc[mt][nt][4 * g + 2] + bb[2]), sigmoidf_(acc[mt][nt][4 * g + 3] + bb[3]));
;           EPI_LOOP_END
	v_div_scale_f32 v19, s[10:11], v18, v18, 1.0
	v_rcp_f32_e32 v20, v19
	s_nop 0
	v_fma_f32 v21, -v19, v20, 1.0
	v_fmac_f32_e32 v20, v21, v20
	v_div_scale_f32 v21, vcc, 1.0, v18, 1.0
	v_mul_f32_e32 v22, v21, v20
	v_fma_f32 v23, -v19, v22, v21
	v_fmac_f32_e32 v22, v23, v20
	v_fma_f32 v19, -v19, v22, v21
	v_div_fmas_f32 v19, v19, v20, v22
	v_div_fixup_f32 v18, v19, v18, 1.0
	v_cvt_pk_bf16_f32 v135, v18, v0
	v_add_f32_e32 v0, v58, v30
	v_mul_f32_e32 v0, 0xbfb8aa3b, v0
	v_exp_f32_e32 v18, v0
	v_add_f32_e32 v0, v59, v31
	v_mul_f32_e32 v0, 0xbfb8aa3b, v0
	v_exp_f32_e32 v19, v0
	s_nop 0
	v_pk_add_f32 v[18:19], v[18:19], 1.0 op_sel_hi:[1,0]
	s_nop 0
	v_div_scale_f32 v0, s[10:11], v19, v19, 1.0
	v_rcp_f32_e32 v20, v0
	s_nop 0
	v_fma_f32 v21, -v0, v20, 1.0
	v_fmac_f32_e32 v20, v21, v20
	v_div_scale_f32 v21, vcc, 1.0, v19, 1.0
	v_mul_f32_e32 v22, v21, v20
	v_fma_f32 v23, -v0, v22, v21
	v_fmac_f32_e32 v22, v23, v20
	v_fma_f32 v0, -v0, v22, v21
	v_div_fmas_f32 v0, v0, v20, v22
	v_div_fixup_f32 v0, v0, v19, 1.0
	v_div_scale_f32 v19, s[10:11], v18, v18, 1.0
	v_rcp_f32_e32 v20, v19
	s_nop 0
	v_fma_f32 v21, -v19, v20, 1.0
	v_fmac_f32_e32 v20, v21, v20
	v_div_scale_f32 v21, vcc, 1.0, v18, 1.0
	v_mul_f32_e32 v22, v21, v20
	v_fma_f32 v23, -v19, v22, v21
	v_fmac_f32_e32 v22, v23, v20
	v_fma_f32 v19, -v19, v22, v21
	v_div_fmas_f32 v19, v19, v20, v22
	v_div_fixup_f32 v18, v19, v18, 1.0
	v_cvt_pk_bf16_f32 v136, v18, v0
	v_add_f32_e32 v0, v60, v32
	v_mul_f32_e32 v0, 0xbfb8aa3b, v0
	v_exp_f32_e32 v18, v0
	v_add_f32_e32 v0, v61, v33
	v_mul_f32_e32 v0, 0xbfb8aa3b, v0
	v_exp_f32_e32 v19, v0
	s_nop 0
	v_pk_add_f32 v[18:19], v[18:19], 1.0 op_sel_hi:[1,0]
	s_nop 0
	v_div_scale_f32 v0, s[10:11], v19, v19, 1.0
	v_rcp_f32_e32 v20, v0
	s_nop 0
	v_fma_f32 v21, -v0, v20, 1.0
	v_fmac_f32_e32 v20, v21, v20
	v_div_scale_f32 v21, vcc, 1.0, v19, 1.0
	v_mul_f32_e32 v22, v21, v20
	v_fma_f32 v23, -v0, v22, v21
	v_fmac_f32_e32 v22, v23, v20
	v_fma_f32 v0, -v0, v22, v21
	v_div_fmas_f32 v0, v0, v20, v22
	v_div_fixup_f32 v0, v0, v19, 1.0
	v_div_scale_f32 v19, s[10:11], v18, v18, 1.0
	v_rcp_f32_e32 v20, v19
	s_nop 0
	v_fma_f32 v21, -v19, v20, 1.0
	v_fmac_f32_e32 v20, v21, v20
	v_div_scale_f32 v21, vcc, 1.0, v18, 1.0
	v_mul_f32_e32 v22, v21, v20
	v_fma_f32 v23, -v19, v22, v21
	v_fmac_f32_e32 v22, v23, v20
	v_fma_f32 v19, -v19, v22, v21
	v_div_fmas_f32 v19, v19, v20, v22
	v_div_fixup_f32 v18, v19, v18, 1.0
	v_cvt_pk_bf16_f32 v137, v18, v0
	v_add_f32_e32 v0, v62, v2
	v_mul_f32_e32 v0, 0xbfb8aa3b, v0
	v_exp_f32_e32 v2, v0
	v_add_f32_e32 v0, v63, v3
	v_mul_f32_e32 v0, 0xbfb8aa3b, v0
	v_exp_f32_e32 v3, v0
	s_nop 0
	v_pk_add_f32 v[2:3], v[2:3], 1.0 op_sel_hi:[1,0]
	s_nop 0
	v_div_scale_f32 v0, s[10:11], v3, v3, 1.0
	v_rcp_f32_e32 v18, v0
	s_nop 0
	v_fma_f32 v19, -v0, v18, 1.0
	v_fmac_f32_e32 v18, v19, v18
	v_div_scale_f32 v19, vcc, 1.0, v3, 1.0
	v_mul_f32_e32 v20, v19, v18
	v_fma_f32 v21, -v0, v20, v19
	v_fmac_f32_e32 v20, v21, v18
	v_fma_f32 v0, -v0, v20, v19
	v_div_fmas_f32 v0, v0, v18, v20
	v_div_fixup_f32 v0, v0, v3, 1.0
	v_div_scale_f32 v3, s[10:11], v2, v2, 1.0
	v_rcp_f32_e32 v18, v3
	s_nop 0
	v_fma_f32 v19, -v3, v18, 1.0
	v_fmac_f32_e32 v18, v19, v18
	v_div_scale_f32 v19, vcc, 1.0, v2, 1.0
	v_mul_f32_e32 v20, v19, v18
	v_fma_f32 v21, -v3, v20, v19
	v_fmac_f32_e32 v20, v21, v18
	v_fma_f32 v3, -v3, v20, v19
	v_div_fmas_f32 v3, v3, v18, v20
	v_div_fixup_f32 v2, v3, v2, 1.0
	v_cvt_pk_bf16_f32 v140, v2, v0
	v_add_f32_e32 v0, v64, v4
	v_mul_f32_e32 v0, 0xbfb8aa3b, v0
	v_exp_f32_e32 v2, v0
	v_add_f32_e32 v0, v65, v5
	v_mul_f32_e32 v0, 0xbfb8aa3b, v0
	v_exp_f32_e32 v3, v0
	s_nop 0
	v_pk_add_f32 v[2:3], v[2:3], 1.0 op_sel_hi:[1,0]
	s_nop 0
	v_div_scale_f32 v0, s[10:11], v3, v3, 1.0
	v_rcp_f32_e32 v4, v0
	s_nop 0
	v_fma_f32 v5, -v0, v4, 1.0
	v_fmac_f32_e32 v4, v5, v4
	v_div_scale_f32 v5, vcc, 1.0, v3, 1.0
	v_mul_f32_e32 v18, v5, v4
	v_fma_f32 v19, -v0, v18, v5
	v_fmac_f32_e32 v18, v19, v4
	v_fma_f32 v0, -v0, v18, v5
	v_div_fmas_f32 v0, v0, v4, v18
	v_div_fixup_f32 v0, v0, v3, 1.0
	v_div_scale_f32 v3, s[10:11], v2, v2, 1.0
	v_rcp_f32_e32 v4, v3
	s_nop 0
	v_fma_f32 v5, -v3, v4, 1.0
	v_fmac_f32_e32 v4, v5, v4
	v_div_scale_f32 v5, vcc, 1.0, v2, 1.0
	v_mul_f32_e32 v18, v5, v4
	v_fma_f32 v19, -v3, v18, v5
	v_fmac_f32_e32 v18, v19, v4
	v_fma_f32 v3, -v3, v18, v5
	v_div_fmas_f32 v3, v3, v4, v18
	v_div_fixup_f32 v2, v3, v2, 1.0
	v_cvt_pk_bf16_f32 v141, v2, v0
	v_add_f32_e32 v0, v34, v6
	v_mul_f32_e32 v0, 0xbfb8aa3b, v0
	v_exp_f32_e32 v2, v0
	v_add_f32_e32 v0, v35, v7
	v_mul_f32_e32 v0, 0xbfb8aa3b, v0
	v_exp_f32_e32 v3, v0
	v_mov_b32_e32 v34, v159
	v_pk_add_f32 v[2:3], v[2:3], 1.0 op_sel_hi:[1,0]
	s_nop 0
	v_div_scale_f32 v0, s[10:11], v3, v3, 1.0
	v_rcp_f32_e32 v4, v0
	v_bfe_u32 v35, v34, 3, 5
	v_fma_f32 v5, -v0, v4, 1.0
	v_fmac_f32_e32 v4, v5, v4
	v_div_scale_f32 v5, vcc, 1.0, v3, 1.0
	v_mul_f32_e32 v6, v5, v4
	v_fma_f32 v7, -v0, v6, v5
	v_fmac_f32_e32 v6, v7, v4
	v_fma_f32 v0, -v0, v6, v5
	v_div_fmas_f32 v0, v0, v4, v6
	v_div_fixup_f32 v0, v0, v3, 1.0
	v_div_scale_f32 v3, s[10:11], v2, v2, 1.0
	v_rcp_f32_e32 v4, v3
	s_nop 0
	v_fma_f32 v5, -v3, v4, 1.0
	v_fmac_f32_e32 v4, v5, v4
	v_div_scale_f32 v5, vcc, 1.0, v2, 1.0
	v_mul_f32_e32 v6, v5, v4
	v_fma_f32 v7, -v3, v6, v5
	v_fmac_f32_e32 v6, v7, v4
	v_fma_f32 v3, -v3, v6, v5
	v_div_fmas_f32 v3, v3, v4, v6
	v_div_fixup_f32 v2, v3, v2, 1.0
	v_cvt_pk_bf16_f32 v142, v2, v0
	v_add_f32_e32 v0, v36, v8
	v_mul_f32_e32 v0, 0xbfb8aa3b, v0
	v_exp_f32_e32 v2, v0
	v_add_f32_e32 v0, v37, v9
	v_mul_f32_e32 v0, 0xbfb8aa3b, v0
	v_exp_f32_e32 v3, v0
	v_and_b32_e32 v36, 31, v34
	v_pk_add_f32 v[2:3], v[2:3], 1.0 op_sel_hi:[1,0]
	s_nop 0
	v_div_scale_f32 v0, s[10:11], v3, v3, 1.0
; DI float sigmoidf_(float x) { return 1.f / (1.f + __expf(-x)); }
; template <int AMODE, bool SWAP>
; DI void gemm_core(const u16* __restrict__ A, int lda, const u16* __restrict__ Bt, int ldb, int K, int m0, int n0, int acol,
;                   f32x16 (&acc)[2][2], u16* sA, u16* sB) {
;     ...
;   auto gload = [&](int kt, u32x4 (&xa)[4], u32x4 (&xb)[4]) {
; #pragma unroll
;     for (int i = 0; i < 4; ++i) {
;       const int id = tid + 256 * i, row = id >> 3, ch = id & 7;
;       const u16* ap;
;       if (AMODE == 0) ap = A + (size_t)(m0 + row) * lda + kt * 64 + ch * 8;
;       else { int tok = 16 * (m0 + row) + kt; tok = tok < SEQ - 1 ? tok : SEQ - 1; ap = A + (size_t)tok * lda + acol + ch * 8; }
;       xa[i] = *reinterpret_cast<const u32x4*>(ap);
;       xb[i] = *reinterpret_cast<const u32x4*>(Bt + (size_t)(n0 + row) * ldb + kt * 64 + ch * 8);
;     }
;   };
;   auto stage = [&](const u32x4 (&xa)[4], const u32x4 (&xb)[4]) {
; #pragma unroll
;     for (int i = 0; i < 4; ++i) {
;       const int id = tid + 256 * i, row = id >> 3, ch = id & 7;
;       *reinterpret_cast<u32x4*>(sA + row * LDT + ch * 8) = xa[i];
;       *reinterpret_cast<u32x4*>(sB + row * LDT + ch * 8) = xb[i];
;     }
;   };
; __global__ void __launch_bounds__(512, 2) mega(Params P) {
;     ...
;             gatepk[mt][nt][2 * g] = pack2(sigmoidf_(acc[mt][nt][4 * g] + bb[0]), sigmoidf_(acc[mt][nt][4 * g + 1] + bb[1]));
;             gatepk[mt][nt][2 * g + 1] = pack2(sigmoidf_(acc[mt][nt][4 * g + 2] + bb[2]), sigmoidf_(acc[mt][nt][4 * g + 3] + bb[3]));
;           EPI_LOOP_END
;         }
;         zero_acc(acc);
;         gemm_core<0, true>(PB, 256, WPP, 256, 256, m0, n0, 0, acc, sA, sB);
	v_rcp_f32_e32 v4, v0
	s_nop 0
	v_fma_f32 v5, -v0, v4, 1.0
	v_fmac_f32_e32 v4, v5, v4
	v_div_scale_f32 v5, vcc, 1.0, v3, 1.0
	v_mul_f32_e32 v6, v5, v4
	v_fma_f32 v7, -v0, v6, v5
	v_fmac_f32_e32 v6, v7, v4
	v_fma_f32 v0, -v0, v6, v5
	v_div_fmas_f32 v0, v0, v4, v6
	v_div_fixup_f32 v0, v0, v3, 1.0
	v_div_scale_f32 v3, s[10:11], v2, v2, 1.0
	v_rcp_f32_e32 v4, v3
	s_nop 0
	v_fma_f32 v5, -v3, v4, 1.0
	v_fmac_f32_e32 v4, v5, v4
	v_div_scale_f32 v5, vcc, 1.0, v2, 1.0
	v_mul_f32_e32 v6, v5, v4
	v_fma_f32 v7, -v3, v6, v5
	v_fmac_f32_e32 v6, v7, v4
	v_fma_f32 v3, -v3, v6, v5
	v_div_fmas_f32 v3, v3, v4, v6
	v_div_fixup_f32 v2, v3, v2, 1.0
	v_cvt_pk_bf16_f32 v143, v2, v0
	v_add_f32_e32 v0, v38, v10
	v_mul_f32_e32 v0, 0xbfb8aa3b, v0
	v_exp_f32_e32 v2, v0
	v_add_f32_e32 v0, v39, v11
	v_mul_f32_e32 v0, 0xbfb8aa3b, v0
	v_exp_f32_e32 v3, v0
	s_nop 0
	v_pk_add_f32 v[2:3], v[2:3], 1.0 op_sel_hi:[1,0]
	s_nop 0
	v_div_scale_f32 v0, s[10:11], v3, v3, 1.0
	v_rcp_f32_e32 v4, v0
	s_nop 0
	v_fma_f32 v5, -v0, v4, 1.0
	v_fmac_f32_e32 v4, v5, v4
	v_div_scale_f32 v5, vcc, 1.0, v3, 1.0
	v_mul_f32_e32 v6, v5, v4
	v_fma_f32 v7, -v0, v6, v5
	v_fmac_f32_e32 v6, v7, v4
	v_fma_f32 v0, -v0, v6, v5
	v_div_fmas_f32 v0, v0, v4, v6
	v_div_fixup_f32 v0, v0, v3, 1.0
	v_div_scale_f32 v3, s[10:11], v2, v2, 1.0
	v_rcp_f32_e32 v4, v3
	s_nop 0
	v_fma_f32 v5, -v3, v4, 1.0
	v_fmac_f32_e32 v4, v5, v4
	v_div_scale_f32 v5, vcc, 1.0, v2, 1.0
	v_mul_f32_e32 v6, v5, v4
	v_fma_f32 v7, -v3, v6, v5
	v_fmac_f32_e32 v6, v7, v4
	v_fma_f32 v3, -v3, v6, v5
	v_div_fmas_f32 v3, v3, v4, v6
	v_div_fixup_f32 v2, v3, v2, 1.0
	v_cvt_pk_bf16_f32 v144, v2, v0
	v_add_f32_e32 v0, v40, v12
	v_mul_f32_e32 v0, 0xbfb8aa3b, v0
	v_exp_f32_e32 v2, v0
	v_add_f32_e32 v0, v41, v13
	v_mul_f32_e32 v0, 0xbfb8aa3b, v0
	v_exp_f32_e32 v3, v0
	s_nop 0
	v_pk_add_f32 v[2:3], v[2:3], 1.0 op_sel_hi:[1,0]
	s_nop 0
	v_div_scale_f32 v0, s[10:11], v3, v3, 1.0
	v_rcp_f32_e32 v4, v0
	s_nop 0
	v_fma_f32 v5, -v0, v4, 1.0
	v_fmac_f32_e32 v4, v5, v4
	v_div_scale_f32 v5, vcc, 1.0, v3, 1.0
	v_mul_f32_e32 v6, v5, v4
	v_fma_f32 v7, -v0, v6, v5
	v_fmac_f32_e32 v6, v7, v4
	v_fma_f32 v0, -v0, v6, v5
	v_div_fmas_f32 v0, v0, v4, v6
	v_div_fixup_f32 v0, v0, v3, 1.0
	v_div_scale_f32 v3, s[10:11], v2, v2, 1.0
	v_rcp_f32_e32 v4, v3
	s_nop 0
	v_fma_f32 v5, -v3, v4, 1.0
	v_fmac_f32_e32 v4, v5, v4
	v_div_scale_f32 v5, vcc, 1.0, v2, 1.0
	v_mul_f32_e32 v6, v5, v4
	v_fma_f32 v7, -v3, v6, v5
	v_fmac_f32_e32 v6, v7, v4
	v_fma_f32 v3, -v3, v6, v5
	v_div_fmas_f32 v3, v3, v4, v6
	v_div_fixup_f32 v2, v3, v2, 1.0
	v_cvt_pk_bf16_f32 v145, v2, v0
	v_add_f32_e32 v0, v42, v14
	v_mul_f32_e32 v0, 0xbfb8aa3b, v0
	v_exp_f32_e32 v2, v0
	v_add_f32_e32 v0, v43, v15
	v_mul_f32_e32 v0, 0xbfb8aa3b, v0
	v_exp_f32_e32 v3, v0
	s_nop 0
	v_pk_add_f32 v[2:3], v[2:3], 1.0 op_sel_hi:[1,0]
	s_nop 0
	v_div_scale_f32 v0, s[10:11], v3, v3, 1.0
	v_rcp_f32_e32 v4, v0
	s_nop 0
	v_fma_f32 v5, -v0, v4, 1.0
	v_fmac_f32_e32 v4, v5, v4
	v_div_scale_f32 v5, vcc, 1.0, v3, 1.0
	v_mul_f32_e32 v6, v5, v4
	v_fma_f32 v7, -v0, v6, v5
	v_fmac_f32_e32 v6, v7, v4
	v_fma_f32 v0, -v0, v6, v5
	v_div_fmas_f32 v0, v0, v4, v6
	v_div_fixup_f32 v0, v0, v3, 1.0
	v_div_scale_f32 v3, s[10:11], v2, v2, 1.0
	v_rcp_f32_e32 v4, v3
	s_nop 0
	v_fma_f32 v5, -v3, v4, 1.0
	v_fmac_f32_e32 v4, v5, v4
	v_div_scale_f32 v5, vcc, 1.0, v2, 1.0
	v_mul_f32_e32 v6, v5, v4
	v_fma_f32 v7, -v3, v6, v5
	v_fmac_f32_e32 v6, v7, v4
	v_fma_f32 v3, -v3, v6, v5
	v_div_fmas_f32 v3, v3, v4, v6
	v_div_fixup_f32 v2, v3, v2, 1.0
	v_cvt_pk_bf16_f32 v138, v2, v0
	v_add_f32_e32 v0, v44, v16
	v_mul_f32_e32 v0, 0xbfb8aa3b, v0
	v_exp_f32_e32 v2, v0
	v_add_f32_e32 v0, v45, v17
	v_mul_f32_e32 v0, 0xbfb8aa3b, v0
	v_exp_f32_e32 v3, v0
	s_nop 0
	v_pk_add_f32 v[2:3], v[2:3], 1.0 op_sel_hi:[1,0]
	s_nop 0
	v_div_scale_f32 v0, s[10:11], v3, v3, 1.0
	v_rcp_f32_e32 v4, v0
	s_nop 0
	v_fma_f32 v5, -v0, v4, 1.0
	v_fmac_f32_e32 v4, v5, v4
	v_div_scale_f32 v5, vcc, 1.0, v3, 1.0
	v_mul_f32_e32 v6, v5, v4
	v_fma_f32 v7, -v0, v6, v5
	v_fmac_f32_e32 v6, v7, v4
	v_fma_f32 v0, -v0, v6, v5
	v_div_fmas_f32 v0, v0, v4, v6
	v_div_fixup_f32 v0, v0, v3, 1.0
	v_div_scale_f32 v3, s[10:11], v2, v2, 1.0
	v_rcp_f32_e32 v4, v3
	v_readlane_b32 s10, v252, 44
	v_readlane_b32 s11, v252, 45
	v_fma_f32 v5, -v3, v4, 1.0
	v_fmac_f32_e32 v4, v5, v4
	v_div_scale_f32 v5, vcc, 1.0, v2, 1.0
	v_mul_f32_e32 v6, v5, v4
	v_fma_f32 v7, -v3, v6, v5
	v_fmac_f32_e32 v6, v7, v4
	v_fma_f32 v3, -v3, v6, v5
	v_div_fmas_f32 v3, v3, v4, v6
	v_div_fixup_f32 v2, v3, v2, 1.0
	v_cvt_pk_bf16_f32 v139, v2, v0
	v_or_b32_e32 v0, 32, v35
	v_or_b32_e32 v6, s22, v0
	v_or_b32_e32 v8, s21, v0
	v_or_b32_e32 v0, 64, v35
	v_or_b32_e32 v4, s21, v35
	v_or_b32_e32 v10, s22, v0
	v_or_b32_e32 v12, s21, v0
	v_or_b32_e32 v0, 0x60, v35
	v_or_b32_e32 v2, s22, v35
	v_ashrrev_i32_e32 v5, 31, v4
	v_or_b32_e32 v14, s22, v0
	v_or_b32_e32 v16, s21, v0
	v_ashrrev_i32_e32 v3, 31, v2
	v_lshlrev_b64 v[4:5], 9, v[4:5]
	v_ashrrev_i32_e32 v7, 31, v6
	v_ashrrev_i32_e32 v9, 31, v8
	v_ashrrev_i32_e32 v11, 31, v10
	v_ashrrev_i32_e32 v13, 31, v12
	v_ashrrev_i32_e32 v15, 31, v14
	v_ashrrev_i32_e32 v17, 31, v16
	v_lshlrev_b32_e32 v0, 4, v34
	v_lshlrev_b64 v[2:3], 9, v[2:3]
	v_lshl_add_u64 v[4:5], s[10:11], 0, v[4:5]
	v_lshlrev_b64 v[6:7], 9, v[6:7]
	v_lshlrev_b64 v[8:9], 9, v[8:9]
	v_lshlrev_b64 v[10:11], 9, v[10:11]
	v_lshlrev_b64 v[12:13], 9, v[12:13]
	v_lshlrev_b64 v[14:15], 9, v[14:15]
	v_lshlrev_b64 v[16:17], 9, v[16:17]
	v_and_b32_e32 v0, 0x70, v0
	v_lshl_add_u64 v[2:3], s[12:13], 0, v[2:3]
	v_lshl_add_u64 v[6:7], s[12:13], 0, v[6:7]
	v_lshl_add_u64 v[8:9], s[10:11], 0, v[8:9]
	v_lshl_add_u64 v[10:11], s[12:13], 0, v[10:11]
	v_lshl_add_u64 v[12:13], s[10:11], 0, v[12:13]
	v_lshl_add_u64 v[14:15], s[12:13], 0, v[14:15]
	v_lshl_add_u64 v[16:17], s[10:11], 0, v[16:17]
	v_lshl_add_u64 v[100:101], v[4:5], 0, v[0:1]
	v_lshl_add_u64 v[98:99], v[2:3], 0, v[0:1]
	v_lshl_add_u64 v[102:103], v[6:7], 0, v[0:1]
	v_lshl_add_u64 v[104:105], v[8:9], 0, v[0:1]
	v_lshl_add_u64 v[106:107], v[10:11], 0, v[0:1]
	v_lshl_add_u64 v[108:109], v[12:13], 0, v[0:1]
	v_lshl_add_u64 v[110:111], v[14:15], 0, v[0:1]
	v_lshl_add_u64 v[112:113], v[16:17], 0, v[0:1]
	global_load_dwordx4 v[14:17], v[100:101], off
	global_load_dwordx4 v[10:13], v[104:105], off
	global_load_dwordx4 v[6:9], v[108:109], off
	global_load_dwordx4 v[2:5], v[112:113], off
	global_load_dwordx4 v[18:21], v[98:99], off
	global_load_dwordx4 v[22:25], v[102:103], off
	global_load_dwordx4 v[26:29], v[106:107], off
	global_load_dwordx4 v[30:33], v[110:111], off
	v_mul_u32_u24_e32 v35, 0x48, v35
	v_lshlrev_b32_e32 v35, 1, v35
	v_add3_u32 v147, s42, v0, v35
	s_waitcnt vmcnt(3)
	ds_write_b128 v147, v[18:21]
	ds_write_b128 v147, v[14:17] offset:18432
	s_waitcnt vmcnt(2)
	ds_write_b128 v147, v[22:25] offset:4608
	ds_write_b128 v147, v[10:13] offset:23040
	s_waitcnt vmcnt(1)
	ds_write_b128 v147, v[26:29] offset:9216
	ds_write_b128 v147, v[6:9] offset:27648
	s_waitcnt vmcnt(0)
	ds_write_b128 v147, v[30:33] offset:13824
	ds_write_b128 v147, v[2:5] offset:32256
	s_waitcnt lgkmcnt(0)
	s_barrier
; template <int AMODE, bool SWAP>
; DI void gemm_core(const u16* __restrict__ A, int lda, const u16* __restrict__ Bt, int ldb, int K, int m0, int n0, int acol,
;                   f32x16 (&acc)[2][2], u16* sA, u16* sB) {
;     ...
;   gload(0, ra[0], rb[0]);
;   for (int kt = 0; kt < nk; ++kt) {
;     stage(ra[0], rb[0]);
;     __syncthreads();
;     if (kt + 1 < nk) gload(kt + 1, ra[0], rb[0]);
;     __builtin_amdgcn_sched_barrier(0);
;     compute();
;     __syncthreads();
;   }
	global_load_dwordx4 v[82:85], v[98:99], off offset:128
	global_load_dwordx4 v[86:89], v[100:101], off offset:128
	global_load_dwordx4 v[90:93], v[102:103], off offset:128
	global_load_dwordx4 v[94:97], v[104:105], off offset:128
	global_load_dwordx4 v[66:69], v[106:107], off offset:128
	global_load_dwordx4 v[70:73], v[108:109], off offset:128
	global_load_dwordx4 v[74:77], v[110:111], off offset:128
	global_load_dwordx4 v[78:81], v[112:113], off offset:128
	v_lshrrev_b32_e32 v0, 1, v34
	v_and_or_b32 v35, v0, 64, v36
	v_and_b32_e32 v34, 0x5f, v34
	v_mul_u32_u24_e32 v35, 0x90, v35
	v_and_b32_e32 v36, 16, v0
	v_mul_u32_u24_e32 v34, 0x90, v34
	v_add3_u32 v0, s42, v35, v36
	v_add3_u32 v146, s42, v34, v36
	ds_read_b128 v[2:5], v0
	ds_read_b128 v[148:151], v0 offset:32
	ds_read_b128 v[6:9], v146 offset:18432
	ds_read_b128 v[152:155], v146 offset:18464
	ds_read_b128 v[10:13], v0 offset:4608
	ds_read_b128 v[160:163], v0 offset:4640
	ds_read_b128 v[14:17], v146 offset:23040
	ds_read_b128 v[170:173], v146 offset:23072
	s_waitcnt lgkmcnt(5)
	v_mfma_f32_32x32x16_bf16 v[50:65], v[6:9], v[2:5], 0
	s_waitcnt lgkmcnt(1)
	v_mfma_f32_32x32x16_bf16 v[34:49], v[14:17], v[2:5], 0
	v_mfma_f32_32x32x16_bf16 v[18:33], v[6:9], v[10:13], 0
	v_mfma_f32_32x32x16_bf16 v[2:17], v[14:17], v[10:13], 0
	ds_read_b128 v[174:177], v0 offset:64
	ds_read_b128 v[190:193], v0 offset:4672
	ds_read_b128 v[194:197], v146 offset:18496
	ds_read_b128 v[198:201], v146 offset:23104
	v_mfma_f32_32x32x16_bf16 v[50:65], v[152:155], v[148:151], v[50:65]
	s_waitcnt lgkmcnt(4)
	v_mfma_f32_32x32x16_bf16 v[34:49], v[170:173], v[148:151], v[34:49]
	v_mfma_f32_32x32x16_bf16 v[18:33], v[152:155], v[160:163], v[18:33]
	v_mfma_f32_32x32x16_bf16 v[2:17], v[170:173], v[160:163], v[2:17]
	ds_read_b128 v[148:151], v0 offset:96
	ds_read_b128 v[152:155], v0 offset:4704
	ds_read_b128 v[160:163], v146 offset:18528
	ds_read_b128 v[170:173], v146 offset:23136
	s_waitcnt lgkmcnt(0)
	s_barrier
	s_waitcnt vmcnt(7)
	ds_write_b128 v147, v[82:85]
	s_waitcnt vmcnt(6)
	ds_write_b128 v147, v[86:89] offset:18432
	s_waitcnt vmcnt(5)
	ds_write_b128 v147, v[90:93] offset:4608
	s_waitcnt vmcnt(4)
	ds_write_b128 v147, v[94:97] offset:23040
	s_waitcnt vmcnt(3)
	ds_write_b128 v147, v[66:69] offset:9216
	s_waitcnt vmcnt(2)
	ds_write_b128 v147, v[70:73] offset:27648
	s_waitcnt vmcnt(1)
	ds_write_b128 v147, v[74:77] offset:13824
	s_waitcnt vmcnt(0)
	ds_write_b128 v147, v[78:81] offset:32256
	s_waitcnt lgkmcnt(0)
	s_barrier
	global_load_dwordx4 v[66:69], v[98:99], off offset:256
	global_load_dwordx4 v[70:73], v[100:101], off offset:256
	global_load_dwordx4 v[74:77], v[102:103], off offset:256
	global_load_dwordx4 v[78:81], v[104:105], off offset:256
	global_load_dwordx4 v[82:85], v[106:107], off offset:256
	global_load_dwordx4 v[86:89], v[108:109], off offset:256
	global_load_dwordx4 v[90:93], v[110:111], off offset:256
	global_load_dwordx4 v[94:97], v[112:113], off offset:256
	v_mfma_f32_32x32x16_bf16 v[50:65], v[194:197], v[174:177], v[50:65]
	v_mfma_f32_32x32x16_bf16 v[34:49], v[198:201], v[174:177], v[34:49]
	v_mfma_f32_32x32x16_bf16 v[18:33], v[194:197], v[190:193], v[18:33]
	v_mfma_f32_32x32x16_bf16 v[2:17], v[198:201], v[190:193], v[2:17]
	v_mfma_f32_32x32x16_bf16 v[50:65], v[160:163], v[148:151], v[50:65]
	v_mfma_f32_32x32x16_bf16 v[34:49], v[170:173], v[148:151], v[34:49]
	v_mfma_f32_32x32x16_bf16 v[18:33], v[160:163], v[152:155], v[18:33]
	v_mfma_f32_32x32x16_bf16 v[2:17], v[170:173], v[152:155], v[2:17]
	ds_read_b128 v[148:151], v0
	ds_read_b128 v[152:155], v0 offset:32
	ds_read_b128 v[160:163], v146 offset:18432
	ds_read_b128 v[170:173], v146 offset:18464
	ds_read_b128 v[174:177], v0 offset:4608
	ds_read_b128 v[190:193], v0 offset:4640
	ds_read_b128 v[194:197], v146 offset:23040
	ds_read_b128 v[198:201], v146 offset:23072
	s_waitcnt lgkmcnt(5)
	v_mfma_f32_32x32x16_bf16 v[50:65], v[160:163], v[148:151], v[50:65]
	s_waitcnt lgkmcnt(1)
	v_mfma_f32_32x32x16_bf16 v[34:49], v[194:197], v[148:151], v[34:49]
	v_mfma_f32_32x32x16_bf16 v[18:33], v[160:163], v[174:177], v[18:33]
	v_mfma_f32_32x32x16_bf16 v[2:17], v[194:197], v[174:177], v[2:17]
	ds_read_b128 v[148:151], v0 offset:64
	ds_read_b128 v[160:163], v0 offset:4672
	ds_read_b128 v[174:177], v146 offset:18496
	ds_read_b128 v[194:197], v146 offset:23104
	v_mfma_f32_32x32x16_bf16 v[50:65], v[170:173], v[152:155], v[50:65]
	s_waitcnt lgkmcnt(4)
	v_mfma_f32_32x32x16_bf16 v[34:49], v[198:201], v[152:155], v[34:49]
	v_mfma_f32_32x32x16_bf16 v[18:33], v[170:173], v[190:193], v[18:33]
	v_mfma_f32_32x32x16_bf16 v[2:17], v[198:201], v[190:193], v[2:17]
	ds_read_b128 v[152:155], v0 offset:96
	ds_read_b128 v[170:173], v0 offset:4704
	ds_read_b128 v[190:193], v146 offset:18528
	ds_read_b128 v[198:201], v146 offset:23136
	s_waitcnt lgkmcnt(0)
	s_barrier
	s_waitcnt vmcnt(7)
	ds_write_b128 v147, v[66:69]
	s_waitcnt vmcnt(6)
	ds_write_b128 v147, v[70:73] offset:18432
	s_waitcnt vmcnt(5)
	ds_write_b128 v147, v[74:77] offset:4608
	s_waitcnt vmcnt(4)
	ds_write_b128 v147, v[78:81] offset:23040
	s_waitcnt vmcnt(3)
	ds_write_b128 v147, v[82:85] offset:9216
	s_waitcnt vmcnt(2)
	ds_write_b128 v147, v[86:89] offset:27648
	s_waitcnt vmcnt(1)
	ds_write_b128 v147, v[90:93] offset:13824
	s_waitcnt vmcnt(0)
	ds_write_b128 v147, v[94:97] offset:32256
	s_waitcnt lgkmcnt(0)
	s_barrier
; template <int AMODE, bool SWAP>
; DI void gemm_core(const u16* __restrict__ A, int lda, const u16* __restrict__ Bt, int ldb, int K, int m0, int n0, int acol,
;                   f32x16 (&acc)[2][2], u16* sA, u16* sB) {
;     ...
;   auto compute = [&]() {
;     bf16x8 a0[2], b0[2], a1[2], b1[2];
;     ldfrag(0, a0, b0);
;     ldfrag(1, a1, b1);
;     __builtin_amdgcn_sched_barrier(0);
;     mm(a0, b0);
;     __builtin_amdgcn_sched_barrier(0);
;     ldfrag(2, a0, b0);
;     __builtin_amdgcn_sched_barrier(0);
;     mm(a1, b1);
;     __builtin_amdgcn_sched_barrier(0);
;     ldfrag(3, a1, b1);
;     __builtin_amdgcn_sched_barrier(0);
;     mm(a0, b0);
;     mm(a1, b1);
;   };
;   gload(0, ra[0], rb[0]);
;   for (int kt = 0; kt < nk; ++kt) {
;     stage(ra[0], rb[0]);
;     __syncthreads();
;     if (kt + 1 < nk) gload(kt + 1, ra[0], rb[0]);
;     __builtin_amdgcn_sched_barrier(0);
;     compute();
;     __syncthreads();
;   }
	global_load_dwordx4 v[66:69], v[98:99], off offset:384
	global_load_dwordx4 v[70:73], v[100:101], off offset:384
	global_load_dwordx4 v[74:77], v[102:103], off offset:384
	global_load_dwordx4 v[78:81], v[104:105], off offset:384
	global_load_dwordx4 v[82:85], v[106:107], off offset:384
	global_load_dwordx4 v[86:89], v[108:109], off offset:384
	global_load_dwordx4 v[90:93], v[110:111], off offset:384
	global_load_dwordx4 v[94:97], v[112:113], off offset:384
	v_mfma_f32_32x32x16_bf16 v[50:65], v[174:177], v[148:151], v[50:65]
	v_mfma_f32_32x32x16_bf16 v[34:49], v[194:197], v[148:151], v[34:49]
	v_mfma_f32_32x32x16_bf16 v[18:33], v[174:177], v[160:163], v[18:33]
	v_mfma_f32_32x32x16_bf16 v[2:17], v[194:197], v[160:163], v[2:17]
	v_mfma_f32_32x32x16_bf16 v[50:65], v[190:193], v[152:155], v[50:65]
	v_mfma_f32_32x32x16_bf16 v[34:49], v[198:201], v[152:155], v[34:49]
	v_mfma_f32_32x32x16_bf16 v[18:33], v[190:193], v[170:173], v[18:33]
	v_mfma_f32_32x32x16_bf16 v[2:17], v[198:201], v[170:173], v[2:17]
	ds_read_b128 v[98:101], v0
	ds_read_b128 v[102:105], v0 offset:32
	ds_read_b128 v[106:109], v146 offset:18432
	ds_read_b128 v[110:113], v146 offset:18464
	ds_read_b128 v[148:151], v0 offset:4608
	ds_read_b128 v[152:155], v0 offset:4640
	ds_read_b128 v[160:163], v146 offset:23040
	ds_read_b128 v[170:173], v146 offset:23072
	s_waitcnt lgkmcnt(5)
	v_mfma_f32_32x32x16_bf16 v[50:65], v[106:109], v[98:101], v[50:65]
	s_waitcnt lgkmcnt(1)
	v_mfma_f32_32x32x16_bf16 v[34:49], v[160:163], v[98:101], v[34:49]
	v_mfma_f32_32x32x16_bf16 v[18:33], v[106:109], v[148:151], v[18:33]
	v_mfma_f32_32x32x16_bf16 v[2:17], v[160:163], v[148:151], v[2:17]
	ds_read_b128 v[98:101], v0 offset:64
	ds_read_b128 v[106:109], v0 offset:4672
	ds_read_b128 v[148:151], v146 offset:18496
	ds_read_b128 v[160:163], v146 offset:23104
	v_mfma_f32_32x32x16_bf16 v[50:65], v[110:113], v[102:105], v[50:65]
	s_waitcnt lgkmcnt(4)
	v_mfma_f32_32x32x16_bf16 v[34:49], v[170:173], v[102:105], v[34:49]
	v_mfma_f32_32x32x16_bf16 v[18:33], v[110:113], v[152:155], v[18:33]
	v_mfma_f32_32x32x16_bf16 v[2:17], v[170:173], v[152:155], v[2:17]
	ds_read_b128 v[102:105], v0 offset:96
	ds_read_b128 v[110:113], v0 offset:4704
	ds_read_b128 v[152:155], v146 offset:18528
	ds_read_b128 v[170:173], v146 offset:23136
	s_waitcnt lgkmcnt(5)
	v_mfma_f32_32x32x16_bf16 v[50:65], v[148:151], v[98:101], v[50:65]
	s_waitcnt lgkmcnt(0)
	s_barrier
	s_waitcnt vmcnt(7)
	ds_write_b128 v147, v[66:69]
	s_waitcnt vmcnt(6)
	ds_write_b128 v147, v[70:73] offset:18432
	s_waitcnt vmcnt(5)
	ds_write_b128 v147, v[74:77] offset:4608
	s_waitcnt vmcnt(4)
	ds_write_b128 v147, v[78:81] offset:23040
	s_waitcnt vmcnt(3)
	ds_write_b128 v147, v[82:85] offset:9216
	s_waitcnt vmcnt(2)
	ds_write_b128 v147, v[86:89] offset:27648
	s_waitcnt vmcnt(1)
	ds_write_b128 v147, v[90:93] offset:13824
	s_waitcnt vmcnt(0)
	ds_write_b128 v147, v[94:97] offset:32256
	s_waitcnt lgkmcnt(0)
	s_barrier
	v_mfma_f32_32x32x16_bf16 v[34:49], v[160:163], v[98:101], v[34:49]
	v_mfma_f32_32x32x16_bf16 v[18:33], v[148:151], v[106:109], v[18:33]
	v_mfma_f32_32x32x16_bf16 v[2:17], v[160:163], v[106:109], v[2:17]
	v_mfma_f32_32x32x16_bf16 v[50:65], v[152:155], v[102:105], v[50:65]
	v_mfma_f32_32x32x16_bf16 v[34:49], v[170:173], v[102:105], v[34:49]
	v_mfma_f32_32x32x16_bf16 v[18:33], v[152:155], v[110:113], v[18:33]
	v_mfma_f32_32x32x16_bf16 v[2:17], v[170:173], v[110:113], v[2:17]
	ds_read_b128 v[66:69], v0
	ds_read_b128 v[70:73], v0 offset:32
	ds_read_b128 v[74:77], v146 offset:18432
	ds_read_b128 v[78:81], v146 offset:18464
	ds_read_b128 v[82:85], v0 offset:4608
	ds_read_b128 v[86:89], v0 offset:4640
	ds_read_b128 v[90:93], v146 offset:23040
	ds_read_b128 v[94:97], v146 offset:23072
	s_waitcnt lgkmcnt(5)
	v_mfma_f32_32x32x16_bf16 v[50:65], v[74:77], v[66:69], v[50:65]
	s_waitcnt lgkmcnt(1)
	v_mfma_f32_32x32x16_bf16 v[34:49], v[90:93], v[66:69], v[34:49]
	v_mfma_f32_32x32x16_bf16 v[18:33], v[74:77], v[82:85], v[18:33]
	v_mfma_f32_32x32x16_bf16 v[2:17], v[90:93], v[82:85], v[2:17]
	ds_read_b128 v[66:69], v0 offset:64
	ds_read_b128 v[74:77], v0 offset:4672
	ds_read_b128 v[82:85], v146 offset:18496
	ds_read_b128 v[90:93], v146 offset:23104
	v_mfma_f32_32x32x16_bf16 v[50:65], v[78:81], v[70:73], v[50:65]
	s_waitcnt lgkmcnt(4)
	v_mfma_f32_32x32x16_bf16 v[34:49], v[94:97], v[70:73], v[34:49]
	v_mfma_f32_32x32x16_bf16 v[18:33], v[78:81], v[86:89], v[18:33]
	v_mfma_f32_32x32x16_bf16 v[2:17], v[94:97], v[86:89], v[2:17]
	ds_read_b128 v[70:73], v0 offset:96
	ds_read_b128 v[78:81], v0 offset:4704
	ds_read_b128 v[86:89], v146 offset:18528
	ds_read_b128 v[94:97], v146 offset:23136
	s_waitcnt lgkmcnt(5)
	v_mfma_f32_32x32x16_bf16 v[50:65], v[82:85], v[66:69], v[50:65]
	v_mov_b32_e32 v0, v159
	s_waitcnt lgkmcnt(0)
	s_barrier
; DI float bf2f(u16 v) { return __uint_as_float((u32)v << 16); }
; __global__ void __launch_bounds__(512, 2) mega(Params P) {
;     ...
;         EPI_LOOP_BEGIN EPI_SWAP_IDX
;           f32x4* hp = reinterpret_cast<f32x4*>(H + (size_t)m * DM + nb);
;           f32x4 hv = *hp;
;           const u32 g01 = gatepk[mt][nt][2 * g], g23 = gatepk[mt][nt][2 * g + 1];
;           hv[0] += acc[mt][nt][4 * g] * bf2f((u16)(g01 & 0xffffu));
;           hv[1] += acc[mt][nt][4 * g + 1] * bf2f((u16)(g01 >> 16));
;           hv[2] += acc[mt][nt][4 * g + 2] * bf2f((u16)(g23 & 0xffffu));
;           hv[3] += acc[mt][nt][4 * g + 3] * bf2f((u16)(g23 >> 16));
;           *hp = hv;
;         EPI_LOOP_END
	v_readlane_b32 s48, v255, 4
	v_readlane_b32 s60, v255, 16
	v_mfma_f32_32x32x16_bf16 v[34:49], v[90:93], v[66:69], v[34:49]
	v_mov_b32_e32 v66, v159
	v_and_b32_e32 v67, 31, v0
	v_and_b32_e32 v68, 64, v66
	v_lshrrev_b32_e32 v66, 1, v66
	v_and_b32_e32 v66, 64, v66
	v_lshrrev_b32_e32 v0, 3, v0
	v_or3_b32 v66, v66, v67, s22
	v_and_b32_e32 v0, 4, v0
	v_or3_b32 v68, v68, v0, s21
	v_ashrrev_i32_e32 v67, 31, v66
	v_mfma_f32_32x32x16_bf16 v[50:65], v[86:89], v[70:73], v[50:65]
	v_readlane_b32 s61, v255, 17
	v_ashrrev_i32_e32 v69, 31, v68
	v_lshlrev_b64 v[68:69], 2, v[68:69]
	s_add_i32 s2, s2, 1
	s_mov_b64 s[30:31], 0
	v_readlane_b32 s49, v255, 5
	v_readlane_b32 s50, v255, 6
	v_mfma_f32_32x32x16_bf16 v[34:49], v[94:97], v[70:73], v[34:49]
	v_lshlrev_b64 v[70:71], 12, v[66:67]
	v_lshl_add_u64 v[70:71], s[60:61], 0, v[70:71]
	v_lshl_add_u64 v[70:71], v[70:71], 0, v[68:69]
	v_readlane_b32 s51, v255, 7
	v_readlane_b32 s52, v255, 8
	v_readlane_b32 s53, v255, 9
	v_readlane_b32 s54, v255, 10
	v_mfma_f32_32x32x16_bf16 v[18:33], v[82:85], v[74:77], v[18:33]
	v_readlane_b32 s55, v255, 11
	v_readlane_b32 s56, v255, 12
	v_readlane_b32 s57, v255, 13
	v_readlane_b32 s58, v255, 14
	v_readlane_b32 s59, v255, 15
	v_readlane_b32 s62, v255, 18
	v_readlane_b32 s63, v255, 19
	v_mfma_f32_32x32x16_bf16 v[2:17], v[90:93], v[74:77], v[2:17]
	global_load_dwordx4 v[72:75], v[70:71], off
	global_load_dwordx4 v[202:205], v[70:71], off offset:32
	global_load_dwordx4 v[206:209], v[70:71], off offset:64
	global_load_dwordx4 v[210:213], v[70:71], off offset:96
	global_load_dwordx4 v[214:217], v[70:71], off offset:128
	global_load_dwordx4 v[218:221], v[70:71], off offset:160
	global_load_dwordx4 v[222:225], v[70:71], off offset:192
	v_lshlrev_b32_e32 v76, 16, v114
	v_and_b32_e32 v77, 0xffff0000, v114
	s_waitcnt vmcnt(0)
	v_fma_f32 v50, v50, v76, v72
	v_fma_f32 v51, v51, v77, v73
	v_lshlrev_b32_e32 v72, 16, v115
	v_and_b32_e32 v73, 0xffff0000, v115
	v_pk_fma_f32 v[52:53], v[52:53], v[72:73], v[74:75]
	global_store_dwordx4 v[70:71], v[50:53], off
	s_nop 1
	v_mov_b64_e32 v[50:51], v[202:203]
	v_mov_b64_e32 v[52:53], v[204:205]
	v_lshlrev_b32_e32 v72, 16, v116
	v_and_b32_e32 v73, 0xffff0000, v116
	v_mfma_f32_32x32x16_bf16 v[18:33], v[86:89], v[78:81], v[18:33]
	v_fma_f32 v50, v54, v72, v50
	v_fma_f32 v51, v55, v73, v51
	v_lshlrev_b32_e32 v54, 16, v117
	v_and_b32_e32 v55, 0xffff0000, v117
	v_pk_fma_f32 v[52:53], v[56:57], v[54:55], v[52:53]
	global_store_dwordx4 v[70:71], v[50:53], off offset:32
	s_nop 1
	v_mov_b64_e32 v[50:51], v[206:207]
	v_mov_b64_e32 v[52:53], v[208:209]
	v_lshlrev_b32_e32 v54, 16, v118
	v_and_b32_e32 v55, 0xffff0000, v118
	v_mfma_f32_32x32x16_bf16 v[2:17], v[94:97], v[78:81], v[2:17]
	v_fma_f32 v50, v58, v54, v50
	v_fma_f32 v51, v59, v55, v51
	v_lshlrev_b32_e32 v54, 16, v119
	v_and_b32_e32 v55, 0xffff0000, v119
	v_pk_fma_f32 v[52:53], v[60:61], v[54:55], v[52:53]
	global_store_dwordx4 v[70:71], v[50:53], off offset:64
	s_nop 1
	v_mov_b64_e32 v[50:51], v[210:211]
	v_mov_b64_e32 v[52:53], v[212:213]
	v_lshlrev_b32_e32 v54, 16, v120
	v_and_b32_e32 v55, 0xffff0000, v120
	v_pk_fma_f32 v[50:51], v[62:63], v[54:55], v[50:51]
	v_lshlrev_b32_e32 v54, 16, v121
	v_and_b32_e32 v55, 0xffff0000, v121
	v_pk_fma_f32 v[52:53], v[64:65], v[54:55], v[52:53]
	global_store_dwordx4 v[70:71], v[50:53], off offset:96
	s_nop 1
	v_mov_b64_e32 v[50:51], v[214:215]
	v_mov_b64_e32 v[52:53], v[216:217]
	v_lshlrev_b32_e32 v54, 16, v122
	v_and_b32_e32 v55, 0xffff0000, v122
	v_pk_fma_f32 v[34:35], v[34:35], v[54:55], v[50:51]
	v_lshlrev_b32_e32 v50, 16, v123
	v_and_b32_e32 v51, 0xffff0000, v123
	v_pk_fma_f32 v[36:37], v[36:37], v[50:51], v[52:53]
	global_store_dwordx4 v[70:71], v[34:37], off offset:128
	s_nop 1
	v_mov_b64_e32 v[34:35], v[218:219]
	v_mov_b64_e32 v[36:37], v[220:221]
	v_lshlrev_b32_e32 v50, 16, v124
	v_and_b32_e32 v51, 0xffff0000, v124
	v_pk_fma_f32 v[34:35], v[38:39], v[50:51], v[34:35]
	v_lshlrev_b32_e32 v38, 16, v125
	v_and_b32_e32 v39, 0xffff0000, v125
	v_pk_fma_f32 v[36:37], v[40:41], v[38:39], v[36:37]
	global_store_dwordx4 v[70:71], v[34:37], off offset:160
	s_nop 1
	v_mov_b64_e32 v[34:35], v[222:223]
	v_mov_b64_e32 v[36:37], v[224:225]
	v_lshlrev_b32_e32 v38, 16, v126
	v_and_b32_e32 v39, 0xffff0000, v126
	v_lshlrev_b32_e32 v40, 16, v130
	v_and_b32_e32 v41, 0xffff0000, v130
	v_pk_fma_f32 v[34:35], v[42:43], v[38:39], v[34:35]
	v_lshlrev_b32_e32 v38, 16, v127
	v_and_b32_e32 v39, 0xffff0000, v127
	v_pk_fma_f32 v[36:37], v[44:45], v[38:39], v[36:37]
	global_store_dwordx4 v[70:71], v[34:37], off offset:192
	global_load_dwordx4 v[34:37], v[70:71], off offset:224
	v_lshlrev_b32_e32 v38, 16, v128
	v_and_b32_e32 v39, 0xffff0000, v128
	s_waitcnt vmcnt(0)
; DI float bf2f(u16 v) { return __uint_as_float((u32)v << 16); }
; __global__ void __launch_bounds__(512, 2) mega(Params P) {
;     ...
;         EPI_LOOP_BEGIN EPI_SWAP_IDX
;           f32x4* hp = reinterpret_cast<f32x4*>(H + (size_t)m * DM + nb);
;           f32x4 hv = *hp;
;           const u32 g01 = gatepk[mt][nt][2 * g], g23 = gatepk[mt][nt][2 * g + 1];
;           hv[0] += acc[mt][nt][4 * g] * bf2f((u16)(g01 & 0xffffu));
;           hv[1] += acc[mt][nt][4 * g + 1] * bf2f((u16)(g01 >> 16));
;           hv[2] += acc[mt][nt][4 * g + 2] * bf2f((u16)(g23 & 0xffffu));
;           hv[3] += acc[mt][nt][4 * g + 3] * bf2f((u16)(g23 >> 16));
;           *hp = hv;
;         EPI_LOOP_END
	v_pk_fma_f32 v[34:35], v[46:47], v[38:39], v[34:35]
	v_lshlrev_b32_e32 v38, 16, v129
	v_and_b32_e32 v39, 0xffff0000, v129
	v_pk_fma_f32 v[36:37], v[48:49], v[38:39], v[36:37]
	global_store_dwordx4 v[70:71], v[34:37], off offset:224
	s_nop 1
	v_or_b32_e32 v34, 32, v66
	v_ashrrev_i32_e32 v35, 31, v34
	v_lshlrev_b64 v[34:35], 12, v[34:35]
	v_lshl_add_u64 v[34:35], s[60:61], 0, v[34:35]
	v_lshl_add_u64 v[34:35], v[34:35], 0, v[68:69]
	global_load_dwordx4 v[36:39], v[34:35], off
	global_load_dwordx4 v[202:205], v[34:35], off offset:32
	global_load_dwordx4 v[206:209], v[34:35], off offset:64
	global_load_dwordx4 v[210:213], v[34:35], off offset:96
	global_load_dwordx4 v[214:217], v[34:35], off offset:128
	global_load_dwordx4 v[218:221], v[34:35], off offset:160
	global_load_dwordx4 v[222:225], v[34:35], off offset:192
	s_waitcnt vmcnt(0)
	v_pk_fma_f32 v[18:19], v[18:19], v[40:41], v[36:37]
	v_lshlrev_b32_e32 v36, 16, v131
	v_and_b32_e32 v37, 0xffff0000, v131
	v_pk_fma_f32 v[20:21], v[20:21], v[36:37], v[38:39]
	global_store_dwordx4 v[34:35], v[18:21], off
	s_nop 1
	v_mov_b64_e32 v[18:19], v[202:203]
	v_mov_b64_e32 v[20:21], v[204:205]
	v_lshlrev_b32_e32 v36, 16, v132
	v_and_b32_e32 v37, 0xffff0000, v132
	v_pk_fma_f32 v[18:19], v[22:23], v[36:37], v[18:19]
	v_lshlrev_b32_e32 v22, 16, v133
	v_and_b32_e32 v23, 0xffff0000, v133
	v_pk_fma_f32 v[20:21], v[24:25], v[22:23], v[20:21]
	global_store_dwordx4 v[34:35], v[18:21], off offset:32
	s_nop 1
	v_mov_b64_e32 v[18:19], v[206:207]
	v_mov_b64_e32 v[20:21], v[208:209]
	v_lshlrev_b32_e32 v22, 16, v134
	v_and_b32_e32 v23, 0xffff0000, v134
	v_pk_fma_f32 v[18:19], v[26:27], v[22:23], v[18:19]
	v_lshlrev_b32_e32 v22, 16, v135
	v_and_b32_e32 v23, 0xffff0000, v135
	v_pk_fma_f32 v[20:21], v[28:29], v[22:23], v[20:21]
	global_store_dwordx4 v[34:35], v[18:21], off offset:64
	s_nop 1
	v_mov_b64_e32 v[18:19], v[210:211]
	v_mov_b64_e32 v[20:21], v[212:213]
	v_lshlrev_b32_e32 v22, 16, v136
	v_and_b32_e32 v23, 0xffff0000, v136
	v_pk_fma_f32 v[18:19], v[30:31], v[22:23], v[18:19]
	v_lshlrev_b32_e32 v22, 16, v137
	v_and_b32_e32 v23, 0xffff0000, v137
	v_pk_fma_f32 v[20:21], v[32:33], v[22:23], v[20:21]
	global_store_dwordx4 v[34:35], v[18:21], off offset:96
	s_nop 1
	v_mov_b64_e32 v[18:19], v[214:215]
	v_mov_b64_e32 v[20:21], v[216:217]
	v_lshlrev_b32_e32 v22, 16, v140
	v_and_b32_e32 v23, 0xffff0000, v140
	v_pk_fma_f32 v[2:3], v[2:3], v[22:23], v[18:19]
	v_lshlrev_b32_e32 v18, 16, v141
	v_and_b32_e32 v19, 0xffff0000, v141
	v_pk_fma_f32 v[4:5], v[4:5], v[18:19], v[20:21]
	global_store_dwordx4 v[34:35], v[2:5], off offset:128
	s_nop 1
	v_mov_b64_e32 v[2:3], v[218:219]
	v_mov_b64_e32 v[4:5], v[220:221]
	v_lshlrev_b32_e32 v18, 16, v142
	v_and_b32_e32 v19, 0xffff0000, v142
	v_pk_fma_f32 v[2:3], v[6:7], v[18:19], v[2:3]
	v_lshlrev_b32_e32 v6, 16, v143
	v_and_b32_e32 v7, 0xffff0000, v143
	v_pk_fma_f32 v[4:5], v[8:9], v[6:7], v[4:5]
	global_store_dwordx4 v[34:35], v[2:5], off offset:160
	s_nop 1
	v_mov_b64_e32 v[2:3], v[222:223]
	v_mov_b64_e32 v[4:5], v[224:225]
	v_lshlrev_b32_e32 v6, 16, v144
	v_and_b32_e32 v7, 0xffff0000, v144
	v_pk_fma_f32 v[2:3], v[10:11], v[6:7], v[2:3]
	v_lshlrev_b32_e32 v6, 16, v145
	v_and_b32_e32 v7, 0xffff0000, v145
	v_pk_fma_f32 v[4:5], v[12:13], v[6:7], v[4:5]
	global_store_dwordx4 v[34:35], v[2:5], off offset:192
	global_load_dwordx4 v[2:5], v[34:35], off offset:224
	v_lshlrev_b32_e32 v6, 16, v138
	v_and_b32_e32 v7, 0xffff0000, v138
	s_waitcnt vmcnt(0)
	v_pk_fma_f32 v[2:3], v[14:15], v[6:7], v[2:3]
	v_lshlrev_b32_e32 v6, 16, v139
	v_and_b32_e32 v7, 0xffff0000, v139
	v_pk_fma_f32 v[4:5], v[16:17], v[6:7], v[4:5]
	global_store_dwordx4 v[34:35], v[2:5], off offset:224
	s_branch .LBB0_1552
